# RG-LRU: carry-apply + store section renamed onto free high registers (live-ins copied) and interleaved between the MFMAs of the next gate cluster, wave-0 summary block after the cluster
# baseline (speedup 1.0000x reference)
.LBB0_270:
	v_mov_b32_e32 v179, v1
	v_mov_b64_e32 v[180:181], v[2:3]
	v_mov_b64_e32 v[182:183], v[4:5]
	v_mov_b64_e32 v[184:185], v[6:7]
	v_mov_b64_e32 v[186:187], v[8:9]
	v_mov_b64_e32 v[188:189], v[10:11]
	v_mov_b64_e32 v[190:191], v[12:13]
	v_mov_b64_e32 v[192:193], v[14:15]
	v_mov_b64_e32 v[194:195], v[16:17]
	v_mov_b64_e32 v[196:197], v[18:19]
	v_mov_b64_e32 v[198:199], v[20:21]
	v_mov_b64_e32 v[200:201], v[22:23]
	v_mov_b64_e32 v[202:203], v[24:25]
	v_mov_b64_e32 v[204:205], v[26:27]
	v_mov_b64_e32 v[206:207], v[28:29]
	v_mov_b64_e32 v[208:209], v[30:31]
	v_mov_b64_e32 v[210:211], v[32:33]
	v_mov_b64_e32 v[212:213], v[34:35]
	v_mov_b64_e32 v[214:215], v[36:37]
	v_mov_b64_e32 v[216:217], v[38:39]
	v_mov_b64_e32 v[218:219], v[40:41]
	v_mov_b64_e32 v[220:221], v[42:43]
	v_mov_b64_e32 v[222:223], v[44:45]
	v_mov_b64_e32 v[238:239], v[46:47]
	s_setprio 1
	ds_read_b128 v[0:3], v145 offset:24576
	ds_read_b128 v[4:7], v145 offset:57344
	s_waitcnt lgkmcnt(1)
	v_mfma_f32_32x32x16_bf16 v[32:47], v[48:51], v[0:3], 0
	v_cndmask_b32_e64 v178, 1.0, v213, s[4:5]
	v_cndmask_b32_e64 v213, 0, v215, s[4:5]
	v_cndmask_b32_e64 v215, v216, v219, s[4:5]
	v_cndmask_b32_e64 v214, v214, v218, s[4:5]
	v_cndmask_b32_e64 v218, v238, v88, s[4:5]
	v_cndmask_b32_e64 v219, v221, v239, s[4:5]
	s_ashr_i32 s13, s12, 31
	v_lshlrev_b32_e32 v88, 2, v93
	v_fmac_f32_e32 v203, v210, v219
	v_mul_f32_e32 v210, v210, v218
	s_waitcnt lgkmcnt(0)
	v_mfma_f32_32x32x16_bf16 v[16:31], v[48:51], v[4:7], 0
	v_fmac_f32_e32 v187, v212, v214
	v_mul_f32_e32 v212, v212, v215
	v_fmac_f32_e32 v188, v209, v214
	v_mul_f32_e32 v209, v209, v215
	v_fmac_f32_e32 v183, v206, v214
	v_mul_f32_e32 v206, v206, v215
	v_fmac_f32_e32 v189, v196, v214
	v_mul_f32_e32 v196, v196, v215
	v_fmac_f32_e32 v184, v190, v213
	v_mul_f32_e32 v214, v178, v190
	ds_read_b128 v[0:3], v147 offset:24576
	ds_read_b128 v[4:7], v147 offset:57344
	s_waitcnt lgkmcnt(1)
	v_mfma_f32_32x32x16_bf16 v[32:47], v[52:55], v[0:3], v[32:47]
	v_fmac_f32_e32 v182, v191, v213
	v_mul_f32_e32 v215, v178, v191
	v_lshl_add_u64 v[190:191], s[24:25], 0, v[88:89]
	s_lshl_b64 s[6:7], s[12:13], 12
	v_lshl_add_u64 v[94:95], v[190:191], 0, s[6:7]
	v_mul_f32_e32 v191, v210, v186
	v_fmac_f32_e32 v201, v207, v219
	v_mul_f32_e32 v207, v207, v218
	v_fmac_f32_e32 v199, v204, v219
	v_mul_f32_e32 v204, v204, v218
	s_waitcnt lgkmcnt(0)
	v_mfma_f32_32x32x16_bf16 v[16:31], v[52:55], v[4:7], v[16:31]
	v_fmac_f32_e32 v181, v194, v219
	v_mul_f32_e32 v218, v194, v218
	v_lshlrev_b32_e32 v190, 14, v92
	v_fmac_f32_e32 v203, v210, v179
	v_cvt_pk_bf16_f32 v194, v203, v191
	v_mov_b32_e32 v191, v89
	v_cndmask_b32_e64 v216, v220, v223, s[4:5]
	v_cndmask_b32_e64 v217, v217, v222, s[4:5]
	v_lshl_add_u64 v[96:97], v[94:95], 0, v[190:191]
	v_mul_f32_e32 v191, v207, v186
	ds_read_b128 v[0:3], v142 offset:24576
	ds_read_b128 v[4:7], v142 offset:57344
	s_waitcnt lgkmcnt(1)
	v_mfma_f32_32x32x16_bf16 v[32:47], v[56:59], v[0:3], v[32:47]
	v_or_b32_e32 v88, 0x1000, v190
	v_fmac_f32_e32 v200, v211, v217
	v_mul_f32_e32 v211, v211, v216
	v_fmac_f32_e32 v198, v208, v217
	v_mul_f32_e32 v208, v208, v216
	v_fmac_f32_e32 v197, v205, v217
	v_mul_f32_e32 v205, v205, v216
	v_fmac_f32_e32 v185, v195, v217
	v_mul_f32_e32 v216, v195, v216
	v_lshl_or_b32 v175, v138, 2, v133
	s_waitcnt lgkmcnt(0)
	v_mfma_f32_32x32x16_bf16 v[16:31], v[56:59], v[4:7], v[16:31]
	global_load_dword v172, v175, s[42:43]
	global_load_dword v173, v175, s[36:37]
	global_load_dword v174, v175, s[40:41]
	global_store_dword v[96:97], v194, off nt
	v_fmac_f32_e32 v201, v207, v179
	v_cvt_pk_bf16_f32 v191, v201, v191
	v_lshl_add_u64 v[194:195], v[94:95], 0, v[88:89]
	global_store_dword v[194:195], v191, off nt
	v_mul_f32_e32 v191, v204, v186
	v_or_b32_e32 v98, 0x2000, v190
	ds_read_b128 v[0:3], v146 offset:24576
	ds_read_b128 v[4:7], v146 offset:57344
	s_waitcnt lgkmcnt(1)
	v_mfma_f32_32x32x16_bf16 v[32:47], v[60:63], v[0:3], v[32:47]
	v_mov_b32_e32 v99, v89
	v_fmac_f32_e32 v199, v204, v179
	v_cvt_pk_bf16_f32 v191, v199, v191
	v_lshl_add_u64 v[194:195], v[94:95], 0, v[98:99]
	v_fmac_f32_e32 v181, v218, v179
	v_or_b32_e32 v100, 0x3000, v190
	v_mov_b32_e32 v101, v89
	global_store_dword v[194:195], v191, off nt
	v_mul_f32_e32 v191, v218, v186
	v_cvt_pk_bf16_f32 v181, v181, v191
	s_waitcnt lgkmcnt(0)
	v_mfma_f32_32x32x16_bf16 v[16:31], v[60:63], v[4:7], v[16:31]
	v_lshl_add_u64 v[194:195], v[94:95], 0, v[100:101]
	global_store_dword v[194:195], v181, off nt
	v_mul_f32_e32 v181, v211, v186
	v_or_b32_e32 v102, 0x8000, v190
	v_mov_b32_e32 v103, v89
	v_fmac_f32_e32 v200, v211, v179
	v_cvt_pk_bf16_f32 v181, v200, v181
	v_lshl_add_u64 v[194:195], v[94:95], 0, v[102:103]
	global_store_dword v[194:195], v181, off nt
	v_mul_f32_e32 v181, v208, v186
	ds_read_b128 v[0:3], v141 offset:24576
	ds_read_b128 v[4:7], v141 offset:57344
	s_waitcnt lgkmcnt(1)
	v_mfma_f32_32x32x16_bf16 v[32:47], v[64:67], v[0:3], v[32:47]
	v_or_b32_e32 v104, 0x9000, v190
	v_mov_b32_e32 v105, v89
	v_fmac_f32_e32 v198, v208, v179
	v_cvt_pk_bf16_f32 v181, v198, v181
	v_lshl_add_u64 v[194:195], v[94:95], 0, v[104:105]
	global_store_dword v[194:195], v181, off nt
	v_mul_f32_e32 v181, v205, v186
	v_or_b32_e32 v106, 0xa000, v190
	v_mov_b32_e32 v107, v89
	v_fmac_f32_e32 v197, v205, v179
	s_waitcnt lgkmcnt(0)
	v_mfma_f32_32x32x16_bf16 v[16:31], v[64:67], v[4:7], v[16:31]
	v_cvt_pk_bf16_f32 v181, v197, v181
	v_lshl_add_u64 v[194:195], v[94:95], 0, v[106:107]
	global_store_dword v[194:195], v181, off nt
	v_mul_f32_e32 v181, v216, v186
	v_or_b32_e32 v108, 0xb000, v190
	v_mov_b32_e32 v109, v89
	v_fmac_f32_e32 v185, v216, v179
	v_cvt_pk_bf16_f32 v181, v185, v181
	v_lshl_add_u64 v[194:195], v[94:95], 0, v[108:109]
	global_store_dword v[194:195], v181, off nt
	ds_read_b128 v[0:3], v144 offset:24576
	ds_read_b128 v[4:7], v144 offset:57344
	s_waitcnt lgkmcnt(1)
	v_mfma_f32_32x32x16_bf16 v[32:47], v[68:71], v[0:3], v[32:47]
	v_mul_f32_e32 v181, v212, v186
	v_or_b32_e32 v110, 0x10000, v190
	v_mov_b32_e32 v111, v89
	v_fmac_f32_e32 v187, v212, v179
	v_cvt_pk_bf16_f32 v181, v187, v181
	v_lshl_add_u64 v[194:195], v[94:95], 0, v[110:111]
	global_store_dword v[194:195], v181, off nt
	v_mul_f32_e32 v181, v209, v186
	v_or_b32_e32 v112, 0x11000, v190
	v_mov_b32_e32 v113, v89
	s_waitcnt lgkmcnt(0)
	v_mfma_f32_32x32x16_bf16 v[16:31], v[68:71], v[4:7], v[16:31]
	v_fmac_f32_e32 v188, v209, v179
	v_cvt_pk_bf16_f32 v181, v188, v181
	v_lshl_add_u64 v[194:195], v[94:95], 0, v[112:113]
	global_store_dword v[194:195], v181, off nt
	v_mul_f32_e32 v181, v206, v186
	v_or_b32_e32 v114, 0x12000, v190
	v_mov_b32_e32 v115, v89
	v_fmac_f32_e32 v183, v206, v179
	v_cvt_pk_bf16_f32 v181, v183, v181
	v_lshl_add_u64 v[194:195], v[94:95], 0, v[114:115]
	ds_read_b128 v[0:3], v139 offset:24576
	ds_read_b128 v[4:7], v139 offset:57344
	s_waitcnt lgkmcnt(1)
	v_mfma_f32_32x32x16_bf16 v[32:47], v[72:75], v[0:3], v[32:47]
	global_store_dword v[194:195], v181, off nt
	v_fmac_f32_e32 v189, v196, v179
	v_mul_f32_e32 v181, v196, v186
	v_or_b32_e32 v116, 0x13000, v190
	v_mov_b32_e32 v117, v89
	v_cvt_pk_bf16_f32 v181, v189, v181
	v_lshl_add_u64 v[188:189], v[94:95], 0, v[116:117]
	global_store_dword v[188:189], v181, off nt
	v_fmac_f32_e32 v184, v214, v179
	v_mul_f32_e32 v181, v214, v186
	s_waitcnt lgkmcnt(0)
	v_mfma_f32_32x32x16_bf16 v[16:31], v[72:75], v[4:7], v[16:31]
	v_or_b32_e32 v118, 0x18000, v190
	v_mov_b32_e32 v119, v89
	v_cvt_pk_bf16_f32 v181, v184, v181
	v_lshl_add_u64 v[184:185], v[94:95], 0, v[118:119]
	global_store_dword v[184:185], v181, off nt
	v_fmac_f32_e32 v182, v215, v179
	v_mul_f32_e32 v181, v215, v186
	v_or_b32_e32 v120, 0x19000, v190
	v_mov_b32_e32 v121, v89
	v_fmac_f32_e32 v180, v192, v213
	ds_read_b128 v[0:3], v143 offset:24576
	ds_read_b128 v[4:7], v143 offset:57344
	s_waitcnt lgkmcnt(1)
	v_mfma_f32_32x32x16_bf16 v[32:47], v[76:79], v[0:3], v[32:47]
	v_mul_f32_e32 v192, v178, v192
	v_cvt_pk_bf16_f32 v181, v182, v181
	v_lshl_add_u64 v[182:183], v[94:95], 0, v[120:121]
	v_fmac_f32_e32 v193, v202, v213
	v_mul_f32_e32 v178, v178, v202
	s_lshl_b32 s8, s65, 11
	global_store_dword v[182:183], v181, off nt
	v_fmac_f32_e32 v180, v192, v179
	v_mul_f32_e32 v181, v192, v186
	v_or_b32_e32 v122, 0x1a000, v190
	s_waitcnt lgkmcnt(0)
	v_mfma_f32_32x32x16_bf16 v[16:31], v[76:79], v[4:7], v[16:31]
	v_mov_b32_e32 v123, v89
	s_or_b32 s8, s8, s76
	v_cvt_pk_bf16_f32 v182, v180, v181
	v_lshl_add_u64 v[180:181], v[94:95], 0, v[122:123]
	v_fmac_f32_e32 v193, v178, v179
	v_mul_f32_e32 v178, v178, v186
	v_or_b32_e32 v124, 0x1b000, v190
	v_mov_b32_e32 v125, v89
	v_cmp_gt_i32_e64 s[6:7], 32, v90
	v_add_u32_e32 v92, s8, v90
	v_mfma_f32_32x32x16_bf16 v[0:15], v[56:59], v[80:83], 0
	global_store_dword v[180:181], v182, off nt
	v_cvt_pk_bf16_f32 v180, v193, v178
	v_lshl_add_u64 v[178:179], v[94:95], 0, v[124:125]
	v_lshl_add_u32 v90, v90, 3, 16
	global_store_dword v[178:179], v180, off nt
	v_mfma_f32_32x32x16_bf16 v[0:15], v[60:63], v[84:87], v[0:15]
	s_setprio 0
	s_and_saveexec_b64 s[8:9], s[6:7]
	s_cbranch_execz .LBB0_272
	ds_read2_b64 v[178:181], v90 offset0:192 offset1:224
	ds_read2_b64 v[182:185], v90 offset0:128 offset1:160
	ds_read2_b64 v[186:189], v90 offset0:64 offset1:96
	ds_read2_b64 v[190:193], v90 offset1:32
	v_ashrrev_i32_e32 v93, 31, v92
	s_waitcnt lgkmcnt(3)
	v_fma_f32 v194, 0, v180, v181
	v_pk_mul_f32 v[180:181], v[180:181], v[178:179]
	v_fma_f32 v178, v178, v194, v179
	s_waitcnt lgkmcnt(2)
	v_fma_f32 v178, v184, v178, v185
	v_fma_f32 v178, v182, v178, v183
	s_waitcnt lgkmcnt(1)
	v_fma_f32 v179, v188, v178, v189
	v_mov_b32_e32 v178, v180
	v_mov_b32_e32 v194, v184
	v_mov_b32_e32 v195, v186
	v_pk_mul_f32 v[180:181], v[180:181], v[184:185]
	v_pk_fma_f32 v[178:179], v[178:179], v[194:195], v[186:187]
	v_pk_mul_f32 v[180:181], v[180:181], v[182:183]
	s_waitcnt lgkmcnt(0)
	v_mov_b32_e32 v189, v192
	v_mov_b32_e32 v181, v179
	v_pk_mul_f32 v[178:179], v[180:181], v[188:189]
	v_pk_fma_f32 v[180:181], v[180:181], v[188:189], v[192:193]
	v_pk_mul_f32 v[178:179], v[178:179], v[186:187]
	v_mov_b32_e32 v182, v192
	v_mov_b32_e32 v180, v178
	v_mov_b32_e32 v183, v190
	v_pk_mul_f32 v[178:179], v[178:179], v[192:193]
	v_pk_fma_f32 v[180:181], v[180:181], v[182:183], v[190:191]
	v_pk_mul_f32 v[178:179], v[178:179], v[190:191]
	s_nop 0
	v_mov_b32_e32 v179, v181
	v_lshl_add_u64 v[180:181], v[92:93], 3, s[30:31]
	global_store_dwordx2 v[180:181], v[178:179], off
.LBB0_272:
	s_or_b64 exec, exec, s[8:9]
	v_lshl_or_b32 v93, v138, 2, v133
	s_waitcnt vmcnt(16)
	ds_read_b32 v251, v167 offset:128
	v_mul_f32_e32 v148, 0xbfb8aa3b, v173
	v_mul_f32_e32 v93, 0xbfb8aa3b, v174
	v_fmamk_f32 v32, v32, 0xbfb8aa3b, v148
	v_fmamk_f32 v16, v16, 0xbfb8aa3b, v93
	v_exp_f32_e32 v32, v32
	v_exp_f32_e32 v150, v16
	v_fmamk_f32 v17, v17, 0xbfb8aa3b, v93
	v_exp_f32_e32 v151, v17
	v_add_f32_e32 v32, 1.0, v32
	v_add_f32_e32 v150, 1.0, v150
	v_rcp_f32_e32 v17, v32
	v_rcp_f32_e32 v32, v150
	v_fmamk_f32 v33, v33, 0xbfb8aa3b, v148
	v_fmamk_f32 v34, v34, 0xbfb8aa3b, v148
	v_exp_f32_e32 v33, v33
	v_exp_f32_e32 v34, v34
	v_add_f32_e32 v33, 1.0, v33
	v_add_f32_e32 v34, 1.0, v34
	v_rcp_f32_e32 v33, v33
	v_rcp_f32_e32 v34, v34
	v_fmamk_f32 v18, v18, 0xbfb8aa3b, v93
	v_fmamk_f32 v19, v19, 0xbfb8aa3b, v93
	v_exp_f32_e32 v18, v18
	s_waitcnt lgkmcnt(0)
	v_mul_f32_e32 v149, 0x3fb8aa3b, v251
	v_mul_f32_e32 v16, v17, v149
	v_mul_f32_e32 v17, v33, v149
	v_exp_f32_e32 v33, v16
	v_mul_f32_e32 v16, v34, v149
	v_exp_f32_e32 v152, v16
	v_fmamk_f32 v16, v35, 0xbfb8aa3b, v148
	v_exp_f32_e32 v16, v16
	v_exp_f32_e32 v150, v17
	v_add_f32_e32 v16, 1.0, v16
	v_rcp_f32_e32 v16, v16
	v_exp_f32_e32 v19, v19
	v_add_f32_e32 v151, 1.0, v151
	v_add_f32_e32 v18, 1.0, v18
	v_mul_f32_e32 v16, v16, v149
	v_exp_f32_e32 v16, v16
	v_fma_f32 v35, -v152, v152, 1.0
	v_rcp_f32_e32 v17, v151
	v_fma_f32 v34, -v33, v33, 1.0
	v_fma_f32 v151, -v150, v150, 1.0
	v_rcp_f32_e32 v18, v18
	v_sqrt_f32_e32 v35, v35
	v_add_f32_e32 v19, 1.0, v19
	v_fma_f32 v153, -v16, v16, 1.0
	v_sqrt_f32_e32 v34, v34
	v_sqrt_f32_e32 v151, v151
	v_rcp_f32_e32 v19, v19
	v_sqrt_f32_e32 v153, v153
	v_mul_f32_e32 v35, v18, v35
	v_fmamk_f32 v18, v36, 0xbfb8aa3b, v148
	v_mul_f32_e32 v32, v32, v34
	v_mul_f32_e32 v34, v17, v151
	v_mul_f32_e32 v17, v19, v153
	v_fmamk_f32 v19, v20, 0xbfb8aa3b, v93
	v_exp_f32_e32 v18, v18
	v_exp_f32_e32 v19, v19
	v_mul_f32_e32 v3, v3, v17
	v_add_f32_e32 v17, 1.0, v18
	v_rcp_f32_e32 v17, v17
	v_add_f32_e32 v18, 1.0, v19
	v_fmamk_f32 v19, v37, 0xbfb8aa3b, v148
	v_exp_f32_e32 v19, v19
	v_mul_f32_e32 v17, v17, v149
	v_exp_f32_e32 v36, v17
	v_add_f32_e32 v17, 1.0, v19
	v_rcp_f32_e32 v17, v17
	v_fmamk_f32 v19, v21, 0xbfb8aa3b, v93
	v_exp_f32_e32 v19, v19
	v_mul_f32_e32 v17, v17, v149
	v_exp_f32_e32 v37, v17
	v_fmamk_f32 v17, v38, 0xbfb8aa3b, v148
	v_exp_f32_e32 v17, v17
	v_fmamk_f32 v23, v23, 0xbfb8aa3b, v93
	v_add_f32_e32 v19, 1.0, v19
	v_fma_f32 v21, -v37, v37, 1.0
	v_add_f32_e32 v17, 1.0, v17
	v_rcp_f32_e32 v17, v17
	v_fma_f32 v20, -v36, v36, 1.0
	v_rcp_f32_e32 v19, v19
	v_mul_f32_e32 v17, v17, v149
	v_exp_f32_e32 v38, v17
	v_fmamk_f32 v17, v39, 0xbfb8aa3b, v148
	v_exp_f32_e32 v17, v17
	v_sqrt_f32_e32 v21, v21
	v_exp_f32_e32 v23, v23
	v_rcp_f32_e32 v18, v18
	v_add_f32_e32 v17, 1.0, v17
	v_rcp_f32_e32 v17, v17
	v_sqrt_f32_e32 v20, v20
	v_add_f32_e32 v23, 1.0, v23
	v_mul_f32_e32 v154, v19, v21
	v_mul_f32_e32 v17, v17, v149
	v_exp_f32_e32 v17, v17
	v_fmamk_f32 v19, v40, 0xbfb8aa3b, v148
	v_rcp_f32_e32 v23, v23
	v_mul_f32_e32 v153, v18, v20
	v_fma_f32 v151, -v17, v17, 1.0
	v_sqrt_f32_e32 v151, v151
	v_fmamk_f32 v20, v24, 0xbfb8aa3b, v93
	v_fmamk_f32 v22, v22, 0xbfb8aa3b, v93
	v_exp_f32_e32 v19, v19
	v_exp_f32_e32 v20, v20
	v_exp_f32_e32 v22, v22
	v_mul_f32_e32 v18, v23, v151
	v_mul_f32_e32 v7, v7, v18
	v_add_f32_e32 v18, 1.0, v19
	v_rcp_f32_e32 v18, v18
	v_add_f32_e32 v19, 1.0, v20
	v_fmamk_f32 v20, v41, 0xbfb8aa3b, v148
	v_add_f32_e32 v22, 1.0, v22
	v_fma_f32 v39, -v38, v38, 1.0
	v_rcp_f32_e32 v22, v22
	v_sqrt_f32_e32 v39, v39
	v_exp_f32_e32 v20, v20
	v_mul_f32_e32 v18, v18, v149
	v_mul_f32_e32 v21, v22, v39
	v_exp_f32_e32 v39, v18
	v_add_f32_e32 v18, 1.0, v20
	v_rcp_f32_e32 v18, v18
	v_fmamk_f32 v20, v25, 0xbfb8aa3b, v93
	v_exp_f32_e32 v20, v20
	v_mul_f32_e32 v18, v18, v149
	v_exp_f32_e32 v40, v18
	v_fmamk_f32 v18, v42, 0xbfb8aa3b, v148
	v_exp_f32_e32 v18, v18
	v_fmamk_f32 v24, v26, 0xbfb8aa3b, v93
	v_fmamk_f32 v26, v27, 0xbfb8aa3b, v93
	v_add_f32_e32 v20, 1.0, v20
	v_add_f32_e32 v18, 1.0, v18
	v_rcp_f32_e32 v18, v18
	v_fma_f32 v23, -v40, v40, 1.0
	v_fma_f32 v22, -v39, v39, 1.0
	v_mul_f32_e32 v18, v18, v149
	v_exp_f32_e32 v41, v18
	v_fmamk_f32 v18, v43, 0xbfb8aa3b, v148
	v_exp_f32_e32 v18, v18
	v_rcp_f32_e32 v20, v20
	v_sqrt_f32_e32 v23, v23
	v_exp_f32_e32 v26, v26
	v_add_f32_e32 v18, 1.0, v18
	v_rcp_f32_e32 v18, v18
	v_rcp_f32_e32 v19, v19
	v_sqrt_f32_e32 v22, v22
	v_add_f32_e32 v26, 1.0, v26
	v_mul_f32_e32 v18, v18, v149
	v_exp_f32_e32 v18, v18
	v_mul_f32_e32 v43, v20, v23
	v_fmamk_f32 v20, v44, 0xbfb8aa3b, v148
	v_rcp_f32_e32 v26, v26
	v_fma_f32 v27, -v18, v18, 1.0
	v_sqrt_f32_e32 v27, v27
	v_mul_f32_e32 v42, v19, v22
	v_fmamk_f32 v22, v28, 0xbfb8aa3b, v93
	v_exp_f32_e32 v20, v20
	v_exp_f32_e32 v22, v22
	v_mul_f32_e32 v19, v26, v27
	v_mul_f32_e32 v11, v11, v19
	v_add_f32_e32 v19, 1.0, v20
	v_rcp_f32_e32 v19, v19
	v_add_f32_e32 v20, 1.0, v22
	v_fmamk_f32 v22, v45, 0xbfb8aa3b, v148
	v_exp_f32_e32 v22, v22
	v_mul_f32_e32 v19, v19, v149
	v_exp_f32_e32 v44, v19
	v_add_f32_e32 v19, 1.0, v22
	v_rcp_f32_e32 v19, v19
	v_exp_f32_e32 v24, v24
	v_fmamk_f32 v22, v29, 0xbfb8aa3b, v93
	v_mul_f32_e32 v19, v19, v149
	v_exp_f32_e32 v45, v19
	v_fmamk_f32 v19, v46, 0xbfb8aa3b, v148
	v_exp_f32_e32 v19, v19
	v_add_f32_e32 v24, 1.0, v24
	v_fma_f32 v25, -v41, v41, 1.0
	v_add_f32_e32 v19, 1.0, v19
	v_rcp_f32_e32 v19, v19
	v_exp_f32_e32 v22, v22
	v_rcp_f32_e32 v24, v24
	v_sqrt_f32_e32 v25, v25
	v_mul_f32_e32 v19, v19, v149
	v_exp_f32_e32 v46, v19
	v_fmamk_f32 v19, v47, 0xbfb8aa3b, v148
	v_add_f32_e32 v22, 1.0, v22
	v_exp_f32_e32 v19, v19
	v_mul_f32_e32 v151, v24, v25
	v_rcp_f32_e32 v24, v22
	v_fma_f32 v22, -v45, v45, 1.0
	v_sqrt_f32_e32 v25, v22
	v_fmamk_f32 v22, v30, 0xbfb8aa3b, v93
	v_exp_f32_e32 v22, v22
	v_add_f32_e32 v19, 1.0, v19
	v_rcp_f32_e32 v19, v19
	v_fma_f32 v27, -v46, v46, 1.0
	v_add_f32_e32 v22, 1.0, v22
	v_rcp_f32_e32 v26, v22
	v_fmamk_f32 v22, v31, 0xbfb8aa3b, v93
	v_mul_f32_e32 v19, v19, v149
	v_exp_f32_e32 v28, v22
	v_exp_f32_e32 v22, v19
	v_sqrt_f32_e32 v19, v27
	v_fma_f32 v23, -v44, v44, 1.0
	v_add_f32_e32 v27, 1.0, v28
	v_fma_f32 v28, -v22, v22, 1.0
	v_rcp_f32_e32 v27, v27
	v_sqrt_f32_e32 v28, v28
	v_rcp_f32_e32 v20, v20
	v_sqrt_f32_e32 v23, v23
	v_mul_f32_e32 v148, v26, v19
	v_mul_f32_e32 v19, v27, v28
	v_fmac_f32_e32 v7, 0, v17
	v_mul_f32_e32 v15, v15, v19
	v_mul_f32_e32 v19, v38, v7
	v_fmac_f32_e32 v19, v6, v21
	v_fmac_f32_e32 v3, 0, v16
	v_mul_f32_e32 v21, v37, v19
	v_mul_f32_e32 v47, v20, v23
	v_mul_f32_e32 v20, v152, v3
	v_fmac_f32_e32 v21, v5, v154
	v_fmac_f32_e32 v15, 0, v22
	v_mul_f32_e32 v93, v24, v25
	v_fmac_f32_e32 v20, v2, v35
	v_mul_f32_e32 v24, v36, v21
	v_fmac_f32_e32 v11, 0, v18
	v_mul_f32_e32 v2, v46, v15
	v_fmac_f32_e32 v24, v4, v153
	v_mul_f32_e32 v4, v41, v11
	v_fmac_f32_e32 v2, v14, v148
	v_fmac_f32_e32 v4, v10, v151
	v_mul_f32_e32 v5, v45, v2
	v_mul_f32_e32 v23, v150, v20
	v_mul_f32_e32 v6, v40, v4
	v_fmac_f32_e32 v5, v13, v93
	v_fmac_f32_e32 v23, v1, v34
	v_fmac_f32_e32 v6, v9, v43
	v_mul_f32_e32 v14, v22, v46
	v_mul_f32_e32 v9, v44, v5
	v_mul_f32_e32 v25, v33, v23
	v_mul_f32_e32 v13, v45, v14
	v_fmac_f32_e32 v9, v12, v47
	v_fmac_f32_e32 v25, v0, v32
	v_mul_f32_e32 v12, v44, v13
	ds_bpermute_b32 v0, v137, v9
	ds_bpermute_b32 v35, v137, v12
	v_mul_f32_e32 v28, v18, v41
	v_mul_f32_e32 v26, v16, v152
	v_mul_f32_e32 v27, v17, v38
	v_mul_f32_e32 v31, v40, v28
	v_mul_f32_e32 v10, v39, v6
	v_mul_f32_e32 v29, v150, v26
	v_mul_f32_e32 v30, v37, v27
	v_fmac_f32_e32 v10, v8, v42
	v_mul_f32_e32 v34, v39, v31
	v_mul_f32_e32 v32, v33, v29
	v_mul_f32_e32 v33, v36, v30
	s_waitcnt lgkmcnt(1)
	v_cndmask_b32_e64 v36, v0, v9, s[4:5]
	v_cndmask_b32_e64 v37, v9, v0, s[4:5]
	ds_bpermute_b32 v0, v137, v34
	ds_bpermute_b32 v40, v137, v10
	s_waitcnt lgkmcnt(2)
	v_cndmask_b32_e64 v8, v12, v35, s[4:5]
	v_fmac_f32_e32 v37, 0, v8
	ds_bpermute_b32 v8, v137, v33
	v_cndmask_b32_e64 v1, v35, v12, s[4:5]
	v_mul_f32_e32 v38, v12, v35
	v_fmac_f32_e32 v36, v1, v37
	s_waitcnt lgkmcnt(2)
	v_cndmask_b32_e64 v1, v0, v34, s[4:5]
	s_waitcnt lgkmcnt(1)
	v_cndmask_b32_e64 v39, v40, v10, s[4:5]
	v_cndmask_b32_e64 v0, v34, v0, s[4:5]
	v_cndmask_b32_e64 v40, v10, v40, s[4:5]
	ds_bpermute_b32 v44, v137, v24
	v_mul_f32_e32 v41, v38, v0
	v_fmac_f32_e32 v40, v0, v36
	v_mul_f32_e32 v42, v1, v41
	v_fmac_f32_e32 v39, v1, v40
	s_waitcnt lgkmcnt(1)
	v_cndmask_b32_e64 v0, v8, v33, s[4:5]
	v_cndmask_b32_e64 v1, v33, v8, s[4:5]
	ds_bpermute_b32 v8, v137, v32
	ds_bpermute_b32 v47, v137, v25
	s_waitcnt lgkmcnt(2)
	v_cndmask_b32_e64 v43, v44, v24, s[4:5]
	v_cndmask_b32_e64 v44, v24, v44, s[4:5]
	v_mul_f32_e32 v45, v1, v42
	v_fmac_f32_e32 v44, v1, v39
	v_mul_f32_e32 v46, v0, v45
	v_fmac_f32_e32 v43, v0, v44
	s_waitcnt lgkmcnt(1)
	v_cndmask_b32_e64 v0, v32, v8, s[4:5]
	s_waitcnt lgkmcnt(0)
	v_cndmask_b32_e64 v47, v25, v47, s[4:5]
	v_mul_f32_e32 v93, v0, v46
	v_fmac_f32_e32 v47, v0, v43
	s_and_saveexec_b64 s[8:9], s[4:5]
	v_mul_f32_e32 v0, v32, v93
	v_fma_f32 v1, v32, v47, v25
	ds_write_b64 v136, v[0:1] offset:2048
	s_or_b64 exec, exec, s[8:9]
	v_cndmask_b32_e64 v0, 0, 1, s[14:15]
	v_cmp_ne_u32_e64 s[8:9], 1, v0
	s_andn2_b64 vcc, exec, s[14:15]
	s_waitcnt lgkmcnt(0)
	s_barrier
	s_cbranch_vccnz .LBB0_277
	v_add3_u32 v148, v140, v91, s93
	v_mov_b32_e32 v8, 1.0
	v_mov_b32_e32 v1, 0
	s_mov_b32 s12, 7

.LBB0_278:
	v_mov_b32_e32 v179, v1
	v_mov_b64_e32 v[180:181], v[2:3]
	v_mov_b64_e32 v[182:183], v[4:5]
	v_mov_b64_e32 v[184:185], v[6:7]
	v_mov_b64_e32 v[186:187], v[8:9]
	v_mov_b64_e32 v[188:189], v[10:11]
	v_mov_b64_e32 v[190:191], v[12:13]
	v_mov_b64_e32 v[192:193], v[14:15]
	v_mov_b64_e32 v[194:195], v[16:17]
	v_mov_b64_e32 v[196:197], v[18:19]
	v_mov_b64_e32 v[198:199], v[20:21]
	v_mov_b64_e32 v[200:201], v[22:23]
	v_mov_b64_e32 v[202:203], v[24:25]
	v_mov_b64_e32 v[204:205], v[26:27]
	v_mov_b64_e32 v[206:207], v[28:29]
	v_mov_b64_e32 v[208:209], v[30:31]
	v_mov_b64_e32 v[210:211], v[32:33]
	v_mov_b64_e32 v[212:213], v[34:35]
	v_mov_b64_e32 v[214:215], v[36:37]
	v_mov_b64_e32 v[216:217], v[38:39]
	v_mov_b64_e32 v[218:219], v[40:41]
	v_mov_b64_e32 v[220:221], v[42:43]
	v_mov_b64_e32 v[222:223], v[44:45]
	v_mov_b64_e32 v[238:239], v[46:47]
	s_setprio 1
	ds_read_b128 v[0:3], v145 offset:32768
	ds_read_b128 v[4:7], v147 offset:32768
	v_add_u32_e32 v8, 0x8000, v147
	s_waitcnt lgkmcnt(1)
	v_mfma_f32_32x32x16_bf16 v[32:47], v[48:51], v[0:3], 0
	v_cndmask_b32_e64 v178, 1.0, v213, s[4:5]
	v_cndmask_b32_e64 v213, 0, v215, s[4:5]
	v_cndmask_b32_e64 v215, v216, v219, s[4:5]
	v_cndmask_b32_e64 v214, v214, v218, s[4:5]
	v_cndmask_b32_e64 v218, v238, v93, s[4:5]
	v_cndmask_b32_e64 v219, v221, v239, s[4:5]
	v_fmac_f32_e32 v203, v210, v219
	v_add_u32_e32 v0, 0x8000, v145
	ds_read_b128 v[0:3], v0 offset:32768
	ds_read_b128 v[8:11], v8 offset:32768
	s_waitcnt lgkmcnt(1)
	v_mfma_f32_32x32x16_bf16 v[16:31], v[48:51], v[0:3], 0
	v_mul_f32_e32 v210, v210, v218
	v_fmac_f32_e32 v201, v207, v219
	v_mul_f32_e32 v207, v207, v218
	v_fmac_f32_e32 v198, v204, v219
	v_mul_f32_e32 v204, v204, v218
	v_fmac_f32_e32 v181, v194, v219
	v_mul_f32_e32 v218, v194, v218
	v_mfma_f32_32x32x16_bf16 v[32:47], v[52:55], v[4:7], v[32:47]
	v_mul_f32_e32 v194, v210, v186
	v_fmac_f32_e32 v203, v210, v179
	v_cvt_pk_bf16_f32 v194, v203, v194
	v_cndmask_b32_e64 v216, v220, v223, s[4:5]
	v_cndmask_b32_e64 v217, v217, v222, s[4:5]
	v_fmac_f32_e32 v188, v212, v214
	v_mul_f32_e32 v212, v212, v215
	ds_read_b128 v[0:3], v142 offset:32768
	ds_read_b128 v[4:7], v146 offset:32768
	s_waitcnt lgkmcnt(2)
	v_mfma_f32_32x32x16_bf16 v[16:31], v[52:55], v[8:11], v[16:31]
	v_fmac_f32_e32 v184, v209, v214
	v_mul_f32_e32 v209, v209, v215
	v_fmac_f32_e32 v182, v206, v214
	v_mul_f32_e32 v206, v206, v215
	v_fmac_f32_e32 v189, v196, v214
	v_mul_f32_e32 v196, v196, v215
	v_fmac_f32_e32 v187, v190, v213
	v_add_u32_e32 v8, 0x8000, v146
	ds_read_b128 v[8:11], v8 offset:32768
	s_waitcnt lgkmcnt(2)
	v_mfma_f32_32x32x16_bf16 v[32:47], v[56:59], v[0:3], v[32:47]
	v_mul_f32_e32 v214, v178, v190
	v_fmac_f32_e32 v183, v191, v213
	v_mul_f32_e32 v215, v178, v191
	v_lshl_add_u64 v[190:191], v[94:95], 0, s[48:49]
	v_lshl_or_b32 v175, v138, 2, v134
	global_load_dword v172, v175, s[42:43]
	global_load_dword v173, v175, s[36:37]
	v_add_u32_e32 v0, 0x8000, v142
	ds_read_b128 v[0:3], v0 offset:32768
	s_waitcnt lgkmcnt(0)
	v_mfma_f32_32x32x16_bf16 v[16:31], v[56:59], v[0:3], v[16:31]
	global_load_dword v174, v175, s[40:41]
	global_store_dword v[96:97], v194, off offset:128 nt
	v_mul_f32_e32 v194, v207, v186
	v_fmac_f32_e32 v202, v211, v217
	v_mul_f32_e32 v211, v211, v216
	v_fmac_f32_e32 v199, v208, v217
	v_mul_f32_e32 v208, v208, v216
	v_mfma_f32_32x32x16_bf16 v[32:47], v[60:63], v[4:7], v[32:47]
	v_fmac_f32_e32 v197, v205, v217
	v_mul_f32_e32 v205, v205, v216
	v_fmac_f32_e32 v185, v195, v217
	v_mul_f32_e32 v216, v195, v216
	v_fmac_f32_e32 v180, v192, v213
	v_mul_f32_e32 v192, v178, v192
	v_fmac_f32_e32 v193, v200, v213
	ds_read_b128 v[0:3], v141 offset:32768
	ds_read_b128 v[4:7], v144 offset:32768
	v_mfma_f32_32x32x16_bf16 v[16:31], v[60:63], v[8:11], v[16:31]
	v_mul_f32_e32 v178, v178, v200
	v_fmac_f32_e32 v201, v207, v179
	v_cvt_pk_bf16_f32 v200, v201, v194
	v_lshl_add_u64 v[194:195], v[190:191], 0, v[88:89]
	global_store_dword v[194:195], v200, off nt
	v_fmac_f32_e32 v198, v204, v179
	v_mul_f32_e32 v194, v204, v186
	v_add_u32_e32 v8, 0x8000, v144
	ds_read_b128 v[8:11], v8 offset:32768
	s_waitcnt lgkmcnt(2)
	v_mfma_f32_32x32x16_bf16 v[32:47], v[64:67], v[0:3], v[32:47]
	v_cvt_pk_bf16_f32 v198, v198, v194
	v_lshl_add_u64 v[194:195], v[190:191], 0, v[98:99]
	global_store_dword v[194:195], v198, off nt
	v_fmac_f32_e32 v181, v218, v179
	v_mul_f32_e32 v194, v218, v186
	v_cvt_pk_bf16_f32 v181, v181, v194
	v_lshl_add_u64 v[194:195], v[190:191], 0, v[100:101]
	v_add_u32_e32 v0, 0x8000, v141
	ds_read_b128 v[0:3], v0 offset:32768
	s_waitcnt lgkmcnt(0)
	v_mfma_f32_32x32x16_bf16 v[16:31], v[64:67], v[0:3], v[16:31]
	global_store_dword v[194:195], v181, off nt
	v_mul_f32_e32 v181, v211, v186
	v_fmac_f32_e32 v202, v211, v179
	v_cvt_pk_bf16_f32 v181, v202, v181
	v_lshl_add_u64 v[194:195], v[190:191], 0, v[102:103]
	global_store_dword v[194:195], v181, off nt
	v_mul_f32_e32 v181, v208, v186
	v_mfma_f32_32x32x16_bf16 v[32:47], v[68:71], v[4:7], v[32:47]
	v_fmac_f32_e32 v199, v208, v179
	v_cvt_pk_bf16_f32 v181, v199, v181
	v_lshl_add_u64 v[194:195], v[190:191], 0, v[104:105]
	global_store_dword v[194:195], v181, off nt
	v_mul_f32_e32 v181, v205, v186
	v_fmac_f32_e32 v197, v205, v179
	v_cvt_pk_bf16_f32 v181, v197, v181
	ds_read_b128 v[0:3], v139 offset:32768
	ds_read_b128 v[4:7], v143 offset:32768
	v_mfma_f32_32x32x16_bf16 v[16:31], v[68:71], v[8:11], v[16:31]
	v_lshl_add_u64 v[194:195], v[190:191], 0, v[106:107]
	global_store_dword v[194:195], v181, off nt
	v_mul_f32_e32 v181, v216, v186
	v_fmac_f32_e32 v185, v216, v179
	v_cvt_pk_bf16_f32 v181, v185, v181
	v_lshl_add_u64 v[194:195], v[190:191], 0, v[108:109]
	global_store_dword v[194:195], v181, off nt
	v_add_u32_e32 v8, 0x8000, v143
	ds_read_b128 v[8:11], v8 offset:32768
	s_waitcnt lgkmcnt(2)
	v_mfma_f32_32x32x16_bf16 v[32:47], v[72:75], v[0:3], v[32:47]
	v_mul_f32_e32 v181, v212, v186
	v_fmac_f32_e32 v188, v212, v179
	v_cvt_pk_bf16_f32 v181, v188, v181
	v_lshl_add_u64 v[194:195], v[190:191], 0, v[110:111]
	global_store_dword v[194:195], v181, off nt
	v_fmac_f32_e32 v184, v209, v179
	v_mul_f32_e32 v181, v209, v186
	v_add_u32_e32 v0, 0x8000, v139
	ds_read_b128 v[0:3], v0 offset:32768
	s_waitcnt lgkmcnt(0)
	v_mfma_f32_32x32x16_bf16 v[16:31], v[72:75], v[0:3], v[16:31]
	v_cvt_pk_bf16_f32 v181, v184, v181
	v_lshl_add_u64 v[184:185], v[190:191], 0, v[112:113]
	global_store_dword v[184:185], v181, off nt
	v_mul_f32_e32 v181, v206, v186
	v_fmac_f32_e32 v182, v206, v179
	v_cvt_pk_bf16_f32 v181, v182, v181
	v_lshl_add_u64 v[184:185], v[190:191], 0, v[114:115]
	v_mfma_f32_32x32x16_bf16 v[32:47], v[76:79], v[4:7], v[32:47]
	global_store_dword v[184:185], v181, off nt
	v_mul_f32_e32 v181, v196, v186
	v_fmac_f32_e32 v189, v196, v179
	v_cvt_pk_bf16_f32 v181, v189, v181
	v_lshl_add_u64 v[184:185], v[190:191], 0, v[116:117]
	global_store_dword v[184:185], v181, off nt
	v_mul_f32_e32 v181, v214, v186
	v_mfma_f32_32x32x16_bf16 v[16:31], v[76:79], v[8:11], v[16:31]
	v_fmac_f32_e32 v187, v214, v179
	v_cvt_pk_bf16_f32 v181, v187, v181
	v_lshl_add_u64 v[184:185], v[190:191], 0, v[118:119]
	global_store_dword v[184:185], v181, off nt
	v_fmac_f32_e32 v183, v215, v179
	v_mul_f32_e32 v181, v215, v186
	v_cvt_pk_bf16_f32 v181, v183, v181
	v_mfma_f32_32x32x16_bf16 v[0:15], v[64:67], v[80:83], 0
	v_lshl_add_u64 v[182:183], v[190:191], 0, v[120:121]
	global_store_dword v[182:183], v181, off nt
	v_fmac_f32_e32 v180, v192, v179
	v_mul_f32_e32 v181, v192, v186
	v_cvt_pk_bf16_f32 v182, v180, v181
	v_lshl_add_u64 v[180:181], v[190:191], 0, v[122:123]
	v_fmac_f32_e32 v193, v178, v179
	v_mfma_f32_32x32x16_bf16 v[0:15], v[68:71], v[84:87], v[0:15]
	v_mul_f32_e32 v178, v178, v186
	global_store_dword v[180:181], v182, off nt
	v_cvt_pk_bf16_f32 v180, v193, v178
	v_lshl_add_u64 v[178:179], v[190:191], 0, v[124:125]
	global_store_dword v[178:179], v180, off nt
	s_setprio 0
	s_and_saveexec_b64 s[12:13], s[6:7]
	s_cbranch_execz .LBB0_280
	v_add_u32_e32 v190, 0x800, v90
	ds_read2_b64 v[178:181], v190 offset0:192 offset1:224
	ds_read2_b64 v[182:185], v190 offset0:128 offset1:160
	ds_read2_b64 v[186:189], v190 offset0:64 offset1:96
	ds_read2_b64 v[190:193], v190 offset1:32
	s_waitcnt lgkmcnt(3)
	v_fma_f32 v194, 0, v180, v181
	v_pk_mul_f32 v[180:181], v[180:181], v[178:179]
	v_fma_f32 v178, v178, v194, v179
	s_waitcnt lgkmcnt(2)
	v_fma_f32 v178, v184, v178, v185
	v_fma_f32 v178, v182, v178, v183
	s_waitcnt lgkmcnt(1)
	v_fma_f32 v179, v188, v178, v189
	v_mov_b32_e32 v178, v180
	v_mov_b32_e32 v194, v184
	v_mov_b32_e32 v195, v186
	v_pk_mul_f32 v[180:181], v[180:181], v[184:185]
	v_pk_fma_f32 v[178:179], v[178:179], v[194:195], v[186:187]
	v_pk_mul_f32 v[180:181], v[180:181], v[182:183]
	s_waitcnt lgkmcnt(0)
	v_mov_b32_e32 v189, v192
	v_mov_b32_e32 v181, v179
	v_pk_mul_f32 v[178:179], v[180:181], v[188:189]
	v_pk_fma_f32 v[180:181], v[180:181], v[188:189], v[192:193]
	v_pk_mul_f32 v[178:179], v[178:179], v[186:187]
	v_mov_b32_e32 v182, v192
	v_mov_b32_e32 v180, v178
	v_mov_b32_e32 v183, v190
	v_pk_mul_f32 v[178:179], v[178:179], v[192:193]
	v_pk_fma_f32 v[180:181], v[180:181], v[182:183], v[190:191]
	v_pk_mul_f32 v[178:179], v[178:179], v[190:191]
	v_add_u32_e32 v180, 32, v92
	v_mov_b32_e32 v179, v181
	v_ashrrev_i32_e32 v181, 31, v180
	v_lshl_add_u64 v[180:181], v[180:181], 3, s[30:31]
	global_store_dwordx2 v[180:181], v[178:179], off
.LBB0_280:
	s_or_b64 exec, exec, s[12:13]
	v_lshl_or_b32 v93, v138, 2, v134
	s_waitcnt vmcnt(16)
	ds_read_b32 v251, v167 offset:256
	v_mul_f32_e32 v148, 0xbfb8aa3b, v173
	v_mul_f32_e32 v93, 0xbfb8aa3b, v174
	v_fmamk_f32 v32, v32, 0xbfb8aa3b, v148
	v_fmamk_f32 v16, v16, 0xbfb8aa3b, v93
	v_exp_f32_e32 v32, v32
	v_exp_f32_e32 v150, v16
	v_fmamk_f32 v17, v17, 0xbfb8aa3b, v93
	v_exp_f32_e32 v151, v17
	v_add_f32_e32 v32, 1.0, v32
	v_add_f32_e32 v150, 1.0, v150
	v_rcp_f32_e32 v17, v32
	v_rcp_f32_e32 v32, v150
	v_fmamk_f32 v33, v33, 0xbfb8aa3b, v148
	v_fmamk_f32 v34, v34, 0xbfb8aa3b, v148
	v_exp_f32_e32 v33, v33
	v_exp_f32_e32 v34, v34
	v_add_f32_e32 v33, 1.0, v33
	v_add_f32_e32 v34, 1.0, v34
	v_rcp_f32_e32 v33, v33
	v_rcp_f32_e32 v34, v34
	v_fmamk_f32 v18, v18, 0xbfb8aa3b, v93
	v_fmamk_f32 v19, v19, 0xbfb8aa3b, v93
	v_exp_f32_e32 v18, v18
	s_waitcnt lgkmcnt(0)
	v_mul_f32_e32 v149, 0x3fb8aa3b, v251
	v_mul_f32_e32 v16, v17, v149
	v_mul_f32_e32 v17, v33, v149
	v_exp_f32_e32 v33, v16
	v_mul_f32_e32 v16, v34, v149
	v_exp_f32_e32 v152, v16
	v_fmamk_f32 v16, v35, 0xbfb8aa3b, v148
	v_exp_f32_e32 v16, v16
	v_exp_f32_e32 v150, v17
	v_add_f32_e32 v16, 1.0, v16
	v_rcp_f32_e32 v16, v16
	v_exp_f32_e32 v19, v19
	v_add_f32_e32 v151, 1.0, v151
	v_add_f32_e32 v18, 1.0, v18
	v_mul_f32_e32 v16, v16, v149
	v_exp_f32_e32 v16, v16
	v_fma_f32 v35, -v152, v152, 1.0
	v_rcp_f32_e32 v17, v151
	v_fma_f32 v34, -v33, v33, 1.0
	v_fma_f32 v151, -v150, v150, 1.0
	v_rcp_f32_e32 v18, v18
	v_sqrt_f32_e32 v35, v35
	v_add_f32_e32 v19, 1.0, v19
	v_fma_f32 v153, -v16, v16, 1.0
	v_sqrt_f32_e32 v34, v34
	v_sqrt_f32_e32 v151, v151
	v_rcp_f32_e32 v19, v19
	v_sqrt_f32_e32 v153, v153
	v_mul_f32_e32 v35, v18, v35
	v_fmamk_f32 v18, v36, 0xbfb8aa3b, v148
	v_mul_f32_e32 v32, v32, v34
	v_mul_f32_e32 v34, v17, v151
	v_mul_f32_e32 v17, v19, v153
	v_fmamk_f32 v19, v20, 0xbfb8aa3b, v93
	v_exp_f32_e32 v18, v18
	v_exp_f32_e32 v19, v19
	v_mul_f32_e32 v3, v3, v17
	v_add_f32_e32 v17, 1.0, v18
	v_rcp_f32_e32 v17, v17
	v_add_f32_e32 v18, 1.0, v19
	v_fmamk_f32 v19, v37, 0xbfb8aa3b, v148
	v_exp_f32_e32 v19, v19
	v_mul_f32_e32 v17, v17, v149
	v_exp_f32_e32 v36, v17
	v_add_f32_e32 v17, 1.0, v19
	v_rcp_f32_e32 v17, v17
	v_fmamk_f32 v19, v21, 0xbfb8aa3b, v93
	v_exp_f32_e32 v19, v19
	v_mul_f32_e32 v17, v17, v149
	v_exp_f32_e32 v37, v17
	v_fmamk_f32 v17, v38, 0xbfb8aa3b, v148
	v_exp_f32_e32 v17, v17
	v_fmamk_f32 v23, v23, 0xbfb8aa3b, v93
	v_add_f32_e32 v19, 1.0, v19
	v_fma_f32 v21, -v37, v37, 1.0
	v_add_f32_e32 v17, 1.0, v17
	v_rcp_f32_e32 v17, v17
	v_fma_f32 v20, -v36, v36, 1.0
	v_rcp_f32_e32 v19, v19
	v_mul_f32_e32 v17, v17, v149
	v_exp_f32_e32 v38, v17
	v_fmamk_f32 v17, v39, 0xbfb8aa3b, v148
	v_exp_f32_e32 v17, v17
	v_sqrt_f32_e32 v21, v21
	v_exp_f32_e32 v23, v23
	v_rcp_f32_e32 v18, v18
	v_add_f32_e32 v17, 1.0, v17
	v_rcp_f32_e32 v17, v17
	v_sqrt_f32_e32 v20, v20
	v_add_f32_e32 v23, 1.0, v23
	v_mul_f32_e32 v154, v19, v21
	v_mul_f32_e32 v17, v17, v149
	v_exp_f32_e32 v17, v17
	v_fmamk_f32 v19, v40, 0xbfb8aa3b, v148
	v_rcp_f32_e32 v23, v23
	v_mul_f32_e32 v153, v18, v20
	v_fma_f32 v151, -v17, v17, 1.0
	v_sqrt_f32_e32 v151, v151
	v_fmamk_f32 v20, v24, 0xbfb8aa3b, v93
	v_fmamk_f32 v22, v22, 0xbfb8aa3b, v93
	v_exp_f32_e32 v19, v19
	v_exp_f32_e32 v20, v20
	v_exp_f32_e32 v22, v22
	v_mul_f32_e32 v18, v23, v151
	v_mul_f32_e32 v7, v7, v18
	v_add_f32_e32 v18, 1.0, v19
	v_rcp_f32_e32 v18, v18
	v_add_f32_e32 v19, 1.0, v20
	v_fmamk_f32 v20, v41, 0xbfb8aa3b, v148
	v_add_f32_e32 v22, 1.0, v22
	v_fma_f32 v39, -v38, v38, 1.0
	v_rcp_f32_e32 v22, v22
	v_sqrt_f32_e32 v39, v39
	v_exp_f32_e32 v20, v20
	v_mul_f32_e32 v18, v18, v149
	v_mul_f32_e32 v21, v22, v39
	v_exp_f32_e32 v39, v18
	v_add_f32_e32 v18, 1.0, v20
	v_rcp_f32_e32 v18, v18
	v_fmamk_f32 v20, v25, 0xbfb8aa3b, v93
	v_exp_f32_e32 v20, v20
	v_mul_f32_e32 v18, v18, v149
	v_exp_f32_e32 v40, v18
	v_fmamk_f32 v18, v42, 0xbfb8aa3b, v148
	v_exp_f32_e32 v18, v18
	v_fmamk_f32 v24, v26, 0xbfb8aa3b, v93
	v_fmamk_f32 v26, v27, 0xbfb8aa3b, v93
	v_add_f32_e32 v20, 1.0, v20
	v_add_f32_e32 v18, 1.0, v18
	v_rcp_f32_e32 v18, v18
	v_fma_f32 v23, -v40, v40, 1.0
	v_fma_f32 v22, -v39, v39, 1.0
	v_mul_f32_e32 v18, v18, v149
	v_exp_f32_e32 v41, v18
	v_fmamk_f32 v18, v43, 0xbfb8aa3b, v148
	v_exp_f32_e32 v18, v18
	v_rcp_f32_e32 v20, v20
	v_sqrt_f32_e32 v23, v23
	v_exp_f32_e32 v26, v26
	v_add_f32_e32 v18, 1.0, v18
	v_rcp_f32_e32 v18, v18
	v_rcp_f32_e32 v19, v19
	v_sqrt_f32_e32 v22, v22
	v_add_f32_e32 v26, 1.0, v26
	v_mul_f32_e32 v18, v18, v149
	v_exp_f32_e32 v18, v18
	v_mul_f32_e32 v43, v20, v23
	v_fmamk_f32 v20, v44, 0xbfb8aa3b, v148
	v_rcp_f32_e32 v26, v26
	v_fma_f32 v27, -v18, v18, 1.0
	v_sqrt_f32_e32 v27, v27
	v_mul_f32_e32 v42, v19, v22
	v_fmamk_f32 v22, v28, 0xbfb8aa3b, v93
	v_exp_f32_e32 v20, v20
	v_exp_f32_e32 v22, v22
	v_mul_f32_e32 v19, v26, v27
	v_mul_f32_e32 v11, v11, v19
	v_add_f32_e32 v19, 1.0, v20
	v_rcp_f32_e32 v19, v19
	v_add_f32_e32 v20, 1.0, v22
	v_fmamk_f32 v22, v45, 0xbfb8aa3b, v148
	v_exp_f32_e32 v22, v22
	v_mul_f32_e32 v19, v19, v149
	v_exp_f32_e32 v44, v19
	v_add_f32_e32 v19, 1.0, v22
	v_rcp_f32_e32 v19, v19
	v_exp_f32_e32 v24, v24
	v_fmamk_f32 v22, v29, 0xbfb8aa3b, v93
	v_mul_f32_e32 v19, v19, v149
	v_exp_f32_e32 v45, v19
	v_fmamk_f32 v19, v46, 0xbfb8aa3b, v148
	v_exp_f32_e32 v19, v19
	v_add_f32_e32 v24, 1.0, v24
	v_fma_f32 v25, -v41, v41, 1.0
	v_add_f32_e32 v19, 1.0, v19
	v_rcp_f32_e32 v19, v19
	v_exp_f32_e32 v22, v22
	v_rcp_f32_e32 v24, v24
	v_sqrt_f32_e32 v25, v25
	v_mul_f32_e32 v19, v19, v149
	v_exp_f32_e32 v46, v19
	v_fmamk_f32 v19, v47, 0xbfb8aa3b, v148
	v_add_f32_e32 v22, 1.0, v22
	v_exp_f32_e32 v19, v19
	v_mul_f32_e32 v151, v24, v25
	v_rcp_f32_e32 v24, v22
	v_fma_f32 v22, -v45, v45, 1.0
	v_sqrt_f32_e32 v25, v22
	v_fmamk_f32 v22, v30, 0xbfb8aa3b, v93
	v_exp_f32_e32 v22, v22
	v_add_f32_e32 v19, 1.0, v19
	v_rcp_f32_e32 v19, v19
	v_fma_f32 v27, -v46, v46, 1.0
	v_add_f32_e32 v22, 1.0, v22
	v_rcp_f32_e32 v26, v22
	v_fmamk_f32 v22, v31, 0xbfb8aa3b, v93
	v_mul_f32_e32 v19, v19, v149
	v_exp_f32_e32 v28, v22
	v_exp_f32_e32 v22, v19
	v_sqrt_f32_e32 v19, v27
	v_fma_f32 v23, -v44, v44, 1.0
	v_add_f32_e32 v27, 1.0, v28
	v_fma_f32 v28, -v22, v22, 1.0
	v_rcp_f32_e32 v27, v27
	v_sqrt_f32_e32 v28, v28
	v_rcp_f32_e32 v20, v20
	v_sqrt_f32_e32 v23, v23
	v_mul_f32_e32 v148, v26, v19
	v_mul_f32_e32 v19, v27, v28
	v_fmac_f32_e32 v7, 0, v17
	v_mul_f32_e32 v15, v15, v19
	v_mul_f32_e32 v19, v38, v7
	v_fmac_f32_e32 v19, v6, v21
	v_fmac_f32_e32 v3, 0, v16
	v_mul_f32_e32 v21, v37, v19
	v_mul_f32_e32 v47, v20, v23
	v_mul_f32_e32 v20, v152, v3
	v_fmac_f32_e32 v21, v5, v154
	v_fmac_f32_e32 v15, 0, v22
	v_mul_f32_e32 v93, v24, v25
	v_fmac_f32_e32 v20, v2, v35
	v_mul_f32_e32 v24, v36, v21
	v_fmac_f32_e32 v11, 0, v18
	v_mul_f32_e32 v2, v46, v15
	v_fmac_f32_e32 v24, v4, v153
	v_mul_f32_e32 v4, v41, v11
	v_fmac_f32_e32 v2, v14, v148
	v_fmac_f32_e32 v4, v10, v151
	v_mul_f32_e32 v5, v45, v2
	v_mul_f32_e32 v23, v150, v20
	v_mul_f32_e32 v6, v40, v4
	v_fmac_f32_e32 v5, v13, v93
	v_fmac_f32_e32 v23, v1, v34
	v_fmac_f32_e32 v6, v9, v43
	v_mul_f32_e32 v14, v22, v46
	v_mul_f32_e32 v9, v44, v5
	v_mul_f32_e32 v25, v33, v23
	v_mul_f32_e32 v13, v45, v14
	v_fmac_f32_e32 v9, v12, v47
	v_fmac_f32_e32 v25, v0, v32
	v_mul_f32_e32 v12, v44, v13
	ds_bpermute_b32 v0, v137, v9
	ds_bpermute_b32 v35, v137, v12
	v_mul_f32_e32 v28, v18, v41
	v_mul_f32_e32 v26, v16, v152
	v_mul_f32_e32 v27, v17, v38
	v_mul_f32_e32 v31, v40, v28
	v_mul_f32_e32 v10, v39, v6
	v_mul_f32_e32 v29, v150, v26
	v_mul_f32_e32 v30, v37, v27
	v_fmac_f32_e32 v10, v8, v42
	v_mul_f32_e32 v34, v39, v31
	v_mul_f32_e32 v32, v33, v29
	v_mul_f32_e32 v33, v36, v30
	s_waitcnt lgkmcnt(1)
	v_cndmask_b32_e64 v36, v0, v9, s[4:5]
	v_cndmask_b32_e64 v37, v9, v0, s[4:5]
	ds_bpermute_b32 v0, v137, v34
	ds_bpermute_b32 v40, v137, v10
	s_waitcnt lgkmcnt(2)
	v_cndmask_b32_e64 v8, v12, v35, s[4:5]
	v_fmac_f32_e32 v37, 0, v8
	ds_bpermute_b32 v8, v137, v33
	v_cndmask_b32_e64 v1, v35, v12, s[4:5]
	v_mul_f32_e32 v38, v12, v35
	v_fmac_f32_e32 v36, v1, v37
	s_waitcnt lgkmcnt(2)
	v_cndmask_b32_e64 v1, v0, v34, s[4:5]
	s_waitcnt lgkmcnt(1)
	v_cndmask_b32_e64 v39, v40, v10, s[4:5]
	v_cndmask_b32_e64 v0, v34, v0, s[4:5]
	v_cndmask_b32_e64 v40, v10, v40, s[4:5]
	ds_bpermute_b32 v44, v137, v24
	v_mul_f32_e32 v41, v38, v0
	v_fmac_f32_e32 v40, v0, v36
	v_mul_f32_e32 v42, v1, v41
	v_fmac_f32_e32 v39, v1, v40
	s_waitcnt lgkmcnt(1)
	v_cndmask_b32_e64 v0, v8, v33, s[4:5]
	v_cndmask_b32_e64 v1, v33, v8, s[4:5]
	ds_bpermute_b32 v8, v137, v32
	ds_bpermute_b32 v47, v137, v25
	s_waitcnt lgkmcnt(2)
	v_cndmask_b32_e64 v43, v44, v24, s[4:5]
	v_cndmask_b32_e64 v44, v24, v44, s[4:5]
	v_mul_f32_e32 v45, v1, v42
	v_fmac_f32_e32 v44, v1, v39
	v_mul_f32_e32 v46, v0, v45
	v_fmac_f32_e32 v43, v0, v44
	s_waitcnt lgkmcnt(1)
	v_cndmask_b32_e64 v0, v32, v8, s[4:5]
	s_waitcnt lgkmcnt(0)
	v_cndmask_b32_e64 v47, v25, v47, s[4:5]
	v_mul_f32_e32 v93, v0, v46
	v_fmac_f32_e32 v47, v0, v43
	s_and_saveexec_b64 s[12:13], s[4:5]
	v_mul_f32_e32 v0, v32, v93
	v_fma_f32 v1, v32, v47, v25
	ds_write_b64 v136, v[0:1] offset:4096
	s_or_b64 exec, exec, s[12:13]
	s_and_b64 vcc, exec, s[8:9]
	s_waitcnt lgkmcnt(0)
	s_barrier
	s_cbranch_vccnz .LBB0_285
	v_add3_u32 v148, v140, v91, s94
	v_mov_b32_e32 v8, 1.0
	v_mov_b32_e32 v1, 0
	s_mov_b32 s12, 7

.LBB0_286:
	v_mov_b32_e32 v179, v1
	v_mov_b64_e32 v[180:181], v[2:3]
	v_mov_b64_e32 v[182:183], v[4:5]
	v_mov_b64_e32 v[184:185], v[6:7]
	v_mov_b64_e32 v[186:187], v[8:9]
	v_mov_b64_e32 v[188:189], v[10:11]
	v_mov_b64_e32 v[190:191], v[12:13]
	v_mov_b64_e32 v[192:193], v[14:15]
	v_mov_b64_e32 v[194:195], v[16:17]
	v_mov_b64_e32 v[196:197], v[18:19]
	v_mov_b64_e32 v[198:199], v[20:21]
	v_mov_b64_e32 v[200:201], v[22:23]
	v_mov_b64_e32 v[202:203], v[24:25]
	v_mov_b64_e32 v[204:205], v[26:27]
	v_mov_b64_e32 v[206:207], v[28:29]
	v_mov_b64_e32 v[208:209], v[30:31]
	v_mov_b64_e32 v[210:211], v[32:33]
	v_mov_b64_e32 v[212:213], v[34:35]
	v_mov_b64_e32 v[214:215], v[36:37]
	v_mov_b64_e32 v[216:217], v[38:39]
	v_mov_b64_e32 v[218:219], v[40:41]
	v_mov_b64_e32 v[220:221], v[42:43]
	v_mov_b64_e32 v[222:223], v[44:45]
	v_mov_b64_e32 v[238:239], v[46:47]
	s_setprio 1
	ds_read_b128 v[0:3], v145 offset:40960
	ds_read_b128 v[4:7], v147 offset:40960
	v_add_u32_e32 v8, 0xa000, v147
	s_waitcnt lgkmcnt(1)
	v_mfma_f32_32x32x16_bf16 v[32:47], v[48:51], v[0:3], 0
	v_cndmask_b32_e64 v178, 1.0, v213, s[4:5]
	v_cndmask_b32_e64 v213, 0, v215, s[4:5]
	v_cndmask_b32_e64 v215, v216, v219, s[4:5]
	v_cndmask_b32_e64 v214, v214, v218, s[4:5]
	v_cndmask_b32_e64 v218, v238, v93, s[4:5]
	v_cndmask_b32_e64 v219, v221, v239, s[4:5]
	v_fmac_f32_e32 v203, v210, v219
	v_add_u32_e32 v0, 0xa000, v145
	ds_read_b128 v[0:3], v0 offset:32768
	ds_read_b128 v[8:11], v8 offset:32768
	s_waitcnt lgkmcnt(1)
	v_mfma_f32_32x32x16_bf16 v[16:31], v[48:51], v[0:3], 0
	v_mul_f32_e32 v210, v210, v218
	v_fmac_f32_e32 v201, v207, v219
	v_mul_f32_e32 v207, v207, v218
	v_fmac_f32_e32 v198, v204, v219
	v_mul_f32_e32 v204, v204, v218
	v_fmac_f32_e32 v181, v194, v219
	v_mul_f32_e32 v218, v194, v218
	v_mfma_f32_32x32x16_bf16 v[32:47], v[52:55], v[4:7], v[32:47]
	v_mul_f32_e32 v194, v210, v186
	v_fmac_f32_e32 v203, v210, v179
	v_cvt_pk_bf16_f32 v194, v203, v194
	v_cndmask_b32_e64 v216, v220, v223, s[4:5]
	v_cndmask_b32_e64 v217, v217, v222, s[4:5]
	v_fmac_f32_e32 v188, v212, v214
	v_mul_f32_e32 v212, v212, v215
	ds_read_b128 v[0:3], v142 offset:40960
	ds_read_b128 v[4:7], v146 offset:40960
	s_waitcnt lgkmcnt(2)
	v_mfma_f32_32x32x16_bf16 v[16:31], v[52:55], v[8:11], v[16:31]
	v_fmac_f32_e32 v184, v209, v214
	v_mul_f32_e32 v209, v209, v215
	v_fmac_f32_e32 v182, v206, v214
	v_mul_f32_e32 v206, v206, v215
	v_fmac_f32_e32 v189, v196, v214
	v_mul_f32_e32 v196, v196, v215
	v_fmac_f32_e32 v187, v190, v213
	v_add_u32_e32 v8, 0xa000, v146
	ds_read_b128 v[8:11], v8 offset:32768
	s_waitcnt lgkmcnt(2)
	v_mfma_f32_32x32x16_bf16 v[32:47], v[56:59], v[0:3], v[32:47]
	v_mul_f32_e32 v214, v178, v190
	v_fmac_f32_e32 v183, v191, v213
	v_mul_f32_e32 v215, v178, v191
	v_lshl_add_u64 v[190:191], v[94:95], 0, s[60:61]
	v_lshl_or_b32 v175, v138, 2, v135
	global_load_dword v172, v175, s[42:43]
	global_load_dword v173, v175, s[36:37]
	v_add_u32_e32 v0, 0xa000, v142
	ds_read_b128 v[0:3], v0 offset:32768
	s_waitcnt lgkmcnt(0)
	v_mfma_f32_32x32x16_bf16 v[16:31], v[56:59], v[0:3], v[16:31]
	global_load_dword v174, v175, s[40:41]
	global_store_dword v[96:97], v194, off offset:256 nt
	v_mul_f32_e32 v194, v207, v186
	v_fmac_f32_e32 v202, v211, v217
	v_mul_f32_e32 v211, v211, v216
	v_fmac_f32_e32 v199, v208, v217
	v_mul_f32_e32 v208, v208, v216
	v_mfma_f32_32x32x16_bf16 v[32:47], v[60:63], v[4:7], v[32:47]
	v_fmac_f32_e32 v197, v205, v217
	v_mul_f32_e32 v205, v205, v216
	v_fmac_f32_e32 v185, v195, v217
	v_mul_f32_e32 v216, v195, v216
	v_fmac_f32_e32 v180, v192, v213
	v_mul_f32_e32 v192, v178, v192
	v_fmac_f32_e32 v193, v200, v213
	ds_read_b128 v[0:3], v141 offset:40960
	ds_read_b128 v[4:7], v144 offset:40960
	v_mfma_f32_32x32x16_bf16 v[16:31], v[60:63], v[8:11], v[16:31]
	v_mul_f32_e32 v178, v178, v200
	v_fmac_f32_e32 v201, v207, v179
	v_cvt_pk_bf16_f32 v200, v201, v194
	v_lshl_add_u64 v[194:195], v[190:191], 0, v[88:89]
	global_store_dword v[194:195], v200, off nt
	v_fmac_f32_e32 v198, v204, v179
	v_mul_f32_e32 v194, v204, v186
	v_add_u32_e32 v8, 0xa000, v144
	ds_read_b128 v[8:11], v8 offset:32768
	s_waitcnt lgkmcnt(2)
	v_mfma_f32_32x32x16_bf16 v[32:47], v[64:67], v[0:3], v[32:47]
	v_cvt_pk_bf16_f32 v198, v198, v194
	v_lshl_add_u64 v[194:195], v[190:191], 0, v[98:99]
	global_store_dword v[194:195], v198, off nt
	v_fmac_f32_e32 v181, v218, v179
	v_mul_f32_e32 v194, v218, v186
	v_cvt_pk_bf16_f32 v181, v181, v194
	v_lshl_add_u64 v[194:195], v[190:191], 0, v[100:101]
	v_add_u32_e32 v0, 0xa000, v141
	ds_read_b128 v[0:3], v0 offset:32768
	s_waitcnt lgkmcnt(0)
	v_mfma_f32_32x32x16_bf16 v[16:31], v[64:67], v[0:3], v[16:31]
	global_store_dword v[194:195], v181, off nt
	v_mul_f32_e32 v181, v211, v186
	v_fmac_f32_e32 v202, v211, v179
	v_cvt_pk_bf16_f32 v181, v202, v181
	v_lshl_add_u64 v[194:195], v[190:191], 0, v[102:103]
	global_store_dword v[194:195], v181, off nt
	v_mul_f32_e32 v181, v208, v186
	v_mfma_f32_32x32x16_bf16 v[32:47], v[68:71], v[4:7], v[32:47]
	v_fmac_f32_e32 v199, v208, v179
	v_cvt_pk_bf16_f32 v181, v199, v181
	v_lshl_add_u64 v[194:195], v[190:191], 0, v[104:105]
	global_store_dword v[194:195], v181, off nt
	v_mul_f32_e32 v181, v205, v186
	v_fmac_f32_e32 v197, v205, v179
	v_cvt_pk_bf16_f32 v181, v197, v181
	ds_read_b128 v[0:3], v139 offset:40960
	ds_read_b128 v[4:7], v143 offset:40960
	v_mfma_f32_32x32x16_bf16 v[16:31], v[68:71], v[8:11], v[16:31]
	v_lshl_add_u64 v[194:195], v[190:191], 0, v[106:107]
	global_store_dword v[194:195], v181, off nt
	v_mul_f32_e32 v181, v216, v186
	v_fmac_f32_e32 v185, v216, v179
	v_cvt_pk_bf16_f32 v181, v185, v181
	v_lshl_add_u64 v[194:195], v[190:191], 0, v[108:109]
	global_store_dword v[194:195], v181, off nt
	v_add_u32_e32 v8, 0xa000, v143
	ds_read_b128 v[8:11], v8 offset:32768
	s_waitcnt lgkmcnt(2)
	v_mfma_f32_32x32x16_bf16 v[32:47], v[72:75], v[0:3], v[32:47]
	v_mul_f32_e32 v181, v212, v186
	v_fmac_f32_e32 v188, v212, v179
	v_cvt_pk_bf16_f32 v181, v188, v181
	v_lshl_add_u64 v[194:195], v[190:191], 0, v[110:111]
	global_store_dword v[194:195], v181, off nt
	v_fmac_f32_e32 v184, v209, v179
	v_mul_f32_e32 v181, v209, v186
	v_add_u32_e32 v0, 0xa000, v139
	ds_read_b128 v[0:3], v0 offset:32768
	s_waitcnt lgkmcnt(0)
	v_mfma_f32_32x32x16_bf16 v[16:31], v[72:75], v[0:3], v[16:31]
	v_cvt_pk_bf16_f32 v181, v184, v181
	v_lshl_add_u64 v[184:185], v[190:191], 0, v[112:113]
	global_store_dword v[184:185], v181, off nt
	v_mul_f32_e32 v181, v206, v186
	v_fmac_f32_e32 v182, v206, v179
	v_cvt_pk_bf16_f32 v181, v182, v181
	v_lshl_add_u64 v[184:185], v[190:191], 0, v[114:115]
	v_mfma_f32_32x32x16_bf16 v[32:47], v[76:79], v[4:7], v[32:47]
	global_store_dword v[184:185], v181, off nt
	v_mul_f32_e32 v181, v196, v186
	v_fmac_f32_e32 v189, v196, v179
	v_cvt_pk_bf16_f32 v181, v189, v181
	v_lshl_add_u64 v[184:185], v[190:191], 0, v[116:117]
	global_store_dword v[184:185], v181, off nt
	v_mul_f32_e32 v181, v214, v186
	v_mfma_f32_32x32x16_bf16 v[16:31], v[76:79], v[8:11], v[16:31]
	v_fmac_f32_e32 v187, v214, v179
	v_cvt_pk_bf16_f32 v181, v187, v181
	v_lshl_add_u64 v[184:185], v[190:191], 0, v[118:119]
	global_store_dword v[184:185], v181, off nt
	v_fmac_f32_e32 v183, v215, v179
	v_mul_f32_e32 v181, v215, v186
	v_cvt_pk_bf16_f32 v181, v183, v181
	v_mfma_f32_32x32x16_bf16 v[0:15], v[72:75], v[80:83], 0
	v_lshl_add_u64 v[182:183], v[190:191], 0, v[120:121]
	global_store_dword v[182:183], v181, off nt
	v_fmac_f32_e32 v180, v192, v179
	v_mul_f32_e32 v181, v192, v186
	v_cvt_pk_bf16_f32 v182, v180, v181
	v_lshl_add_u64 v[180:181], v[190:191], 0, v[122:123]
	v_fmac_f32_e32 v193, v178, v179
	v_mfma_f32_32x32x16_bf16 v[0:15], v[76:79], v[84:87], v[0:15]
	v_mul_f32_e32 v178, v178, v186
	global_store_dword v[180:181], v182, off nt
	v_cvt_pk_bf16_f32 v180, v193, v178
	v_lshl_add_u64 v[178:179], v[190:191], 0, v[124:125]
	global_store_dword v[178:179], v180, off nt
	s_setprio 0
	s_and_saveexec_b64 s[12:13], s[6:7]
	s_cbranch_execz .LBB0_288
	v_add_u32_e32 v190, 0x1000, v90
	ds_read2_b64 v[178:181], v190 offset0:192 offset1:224
	ds_read2_b64 v[182:185], v190 offset0:128 offset1:160
	ds_read2_b64 v[186:189], v190 offset0:64 offset1:96
	ds_read2_b64 v[190:193], v190 offset1:32
	s_waitcnt lgkmcnt(3)
	v_fma_f32 v194, 0, v180, v181
	v_pk_mul_f32 v[180:181], v[180:181], v[178:179]
	v_fma_f32 v178, v178, v194, v179
	s_waitcnt lgkmcnt(2)
	v_fma_f32 v178, v184, v178, v185
	v_fma_f32 v178, v182, v178, v183
	s_waitcnt lgkmcnt(1)
	v_fma_f32 v179, v188, v178, v189
	v_mov_b32_e32 v178, v180
	v_mov_b32_e32 v194, v184
	v_mov_b32_e32 v195, v186
	v_pk_mul_f32 v[180:181], v[180:181], v[184:185]
	v_pk_fma_f32 v[178:179], v[178:179], v[194:195], v[186:187]
	v_pk_mul_f32 v[180:181], v[180:181], v[182:183]
	s_waitcnt lgkmcnt(0)
	v_mov_b32_e32 v189, v192
	v_mov_b32_e32 v181, v179
	v_pk_mul_f32 v[178:179], v[180:181], v[188:189]
	v_pk_fma_f32 v[180:181], v[180:181], v[188:189], v[192:193]
	v_pk_mul_f32 v[178:179], v[178:179], v[186:187]
	v_mov_b32_e32 v182, v192
	v_mov_b32_e32 v180, v178
	v_mov_b32_e32 v183, v190
	v_pk_mul_f32 v[178:179], v[178:179], v[192:193]
	v_pk_fma_f32 v[180:181], v[180:181], v[182:183], v[190:191]
	v_pk_mul_f32 v[178:179], v[178:179], v[190:191]
	v_add_u32_e32 v180, 64, v92
	v_mov_b32_e32 v179, v181
	v_ashrrev_i32_e32 v181, 31, v180
	v_lshl_add_u64 v[180:181], v[180:181], 3, s[30:31]
	global_store_dwordx2 v[180:181], v[178:179], off
.LBB0_288:
	s_or_b64 exec, exec, s[12:13]
	v_lshl_or_b32 v48, v138, 2, v135
	s_waitcnt vmcnt(16)
	ds_read_b32 v251, v167 offset:384
	v_mul_f32_e32 v49, 0xbfb8aa3b, v173
	v_mul_f32_e32 v48, 0xbfb8aa3b, v174
	v_fmamk_f32 v32, v32, 0xbfb8aa3b, v49
	v_fmamk_f32 v16, v16, 0xbfb8aa3b, v48
	v_exp_f32_e32 v32, v32
	v_exp_f32_e32 v51, v16
	v_fmamk_f32 v17, v17, 0xbfb8aa3b, v48
	v_exp_f32_e32 v52, v17
	v_add_f32_e32 v32, 1.0, v32
	v_add_f32_e32 v51, 1.0, v51
	v_rcp_f32_e32 v17, v32
	v_rcp_f32_e32 v32, v51
	v_fmamk_f32 v33, v33, 0xbfb8aa3b, v49
	v_fmamk_f32 v34, v34, 0xbfb8aa3b, v49
	v_exp_f32_e32 v33, v33
	v_exp_f32_e32 v34, v34
	v_add_f32_e32 v33, 1.0, v33
	v_add_f32_e32 v34, 1.0, v34
	v_rcp_f32_e32 v33, v33
	v_rcp_f32_e32 v34, v34
	v_fmamk_f32 v18, v18, 0xbfb8aa3b, v48
	v_fmamk_f32 v19, v19, 0xbfb8aa3b, v48
	v_exp_f32_e32 v18, v18
	s_waitcnt lgkmcnt(0)
	v_mul_f32_e32 v50, 0x3fb8aa3b, v251
	v_mul_f32_e32 v16, v17, v50
	v_mul_f32_e32 v17, v33, v50
	v_exp_f32_e32 v33, v16
	v_mul_f32_e32 v16, v34, v50
	v_exp_f32_e32 v53, v16
	v_fmamk_f32 v16, v35, 0xbfb8aa3b, v49
	v_exp_f32_e32 v16, v16
	v_exp_f32_e32 v51, v17
	v_add_f32_e32 v16, 1.0, v16
	v_rcp_f32_e32 v16, v16
	v_exp_f32_e32 v19, v19
	v_add_f32_e32 v52, 1.0, v52
	v_add_f32_e32 v18, 1.0, v18
	v_mul_f32_e32 v16, v16, v50
	v_exp_f32_e32 v16, v16
	v_fma_f32 v35, -v53, v53, 1.0
	v_rcp_f32_e32 v17, v52
	v_fma_f32 v34, -v33, v33, 1.0
	v_fma_f32 v52, -v51, v51, 1.0
	v_rcp_f32_e32 v18, v18
	v_sqrt_f32_e32 v35, v35
	v_add_f32_e32 v19, 1.0, v19
	v_fma_f32 v54, -v16, v16, 1.0
	v_sqrt_f32_e32 v34, v34
	v_sqrt_f32_e32 v52, v52
	v_rcp_f32_e32 v19, v19
	v_sqrt_f32_e32 v54, v54
	v_mul_f32_e32 v35, v18, v35
	v_fmamk_f32 v18, v36, 0xbfb8aa3b, v49
	v_mul_f32_e32 v32, v32, v34
	v_mul_f32_e32 v34, v17, v52
	v_mul_f32_e32 v17, v19, v54
	v_fmamk_f32 v19, v20, 0xbfb8aa3b, v48
	v_exp_f32_e32 v18, v18
	v_exp_f32_e32 v19, v19
	v_mul_f32_e32 v3, v3, v17
	v_add_f32_e32 v17, 1.0, v18
	v_rcp_f32_e32 v17, v17
	v_add_f32_e32 v18, 1.0, v19
	v_fmamk_f32 v19, v37, 0xbfb8aa3b, v49
	v_exp_f32_e32 v19, v19
	v_mul_f32_e32 v17, v17, v50
	v_exp_f32_e32 v36, v17
	v_add_f32_e32 v17, 1.0, v19
	v_rcp_f32_e32 v17, v17
	v_fmamk_f32 v19, v21, 0xbfb8aa3b, v48
	v_exp_f32_e32 v19, v19
	v_mul_f32_e32 v17, v17, v50
	v_exp_f32_e32 v37, v17
	v_fmamk_f32 v17, v38, 0xbfb8aa3b, v49
	v_exp_f32_e32 v17, v17
	v_fmamk_f32 v23, v23, 0xbfb8aa3b, v48
	v_add_f32_e32 v19, 1.0, v19
	v_fma_f32 v21, -v37, v37, 1.0
	v_add_f32_e32 v17, 1.0, v17
	v_rcp_f32_e32 v17, v17
	v_fma_f32 v20, -v36, v36, 1.0
	v_rcp_f32_e32 v19, v19
	v_mul_f32_e32 v17, v17, v50
	v_exp_f32_e32 v38, v17
	v_fmamk_f32 v17, v39, 0xbfb8aa3b, v49
	v_exp_f32_e32 v17, v17
	v_sqrt_f32_e32 v21, v21
	v_exp_f32_e32 v23, v23
	v_rcp_f32_e32 v18, v18
	v_add_f32_e32 v17, 1.0, v17
	v_rcp_f32_e32 v17, v17
	v_sqrt_f32_e32 v20, v20
	v_add_f32_e32 v23, 1.0, v23
	v_mul_f32_e32 v55, v19, v21
	v_mul_f32_e32 v17, v17, v50
	v_exp_f32_e32 v17, v17
	v_fmamk_f32 v19, v40, 0xbfb8aa3b, v49
	v_rcp_f32_e32 v23, v23
	v_mul_f32_e32 v54, v18, v20
	v_fma_f32 v52, -v17, v17, 1.0
	v_sqrt_f32_e32 v52, v52
	v_fmamk_f32 v20, v24, 0xbfb8aa3b, v48
	v_fmamk_f32 v22, v22, 0xbfb8aa3b, v48
	v_exp_f32_e32 v19, v19
	v_exp_f32_e32 v20, v20
	v_exp_f32_e32 v22, v22
	v_mul_f32_e32 v18, v23, v52
	v_mul_f32_e32 v7, v7, v18
	v_add_f32_e32 v18, 1.0, v19
	v_rcp_f32_e32 v18, v18
	v_add_f32_e32 v19, 1.0, v20
	v_fmamk_f32 v20, v41, 0xbfb8aa3b, v49
	v_add_f32_e32 v22, 1.0, v22
	v_fma_f32 v39, -v38, v38, 1.0
	v_rcp_f32_e32 v22, v22
	v_sqrt_f32_e32 v39, v39
	v_exp_f32_e32 v20, v20
	v_mul_f32_e32 v18, v18, v50
	v_mul_f32_e32 v21, v22, v39
	v_exp_f32_e32 v39, v18
	v_add_f32_e32 v18, 1.0, v20
	v_rcp_f32_e32 v18, v18
	v_fmamk_f32 v20, v25, 0xbfb8aa3b, v48
	v_exp_f32_e32 v20, v20
	v_mul_f32_e32 v18, v18, v50
	v_exp_f32_e32 v40, v18
	v_fmamk_f32 v18, v42, 0xbfb8aa3b, v49
	v_exp_f32_e32 v18, v18
	v_fmamk_f32 v24, v26, 0xbfb8aa3b, v48
	v_fmamk_f32 v26, v27, 0xbfb8aa3b, v48
	v_add_f32_e32 v20, 1.0, v20
	v_add_f32_e32 v18, 1.0, v18
	v_rcp_f32_e32 v18, v18
	v_fma_f32 v23, -v40, v40, 1.0
	v_fma_f32 v22, -v39, v39, 1.0
	v_mul_f32_e32 v18, v18, v50
	v_exp_f32_e32 v41, v18
	v_fmamk_f32 v18, v43, 0xbfb8aa3b, v49
	v_exp_f32_e32 v18, v18
	v_rcp_f32_e32 v20, v20
	v_sqrt_f32_e32 v23, v23
	v_exp_f32_e32 v26, v26
	v_add_f32_e32 v18, 1.0, v18
	v_rcp_f32_e32 v18, v18
	v_rcp_f32_e32 v19, v19
	v_sqrt_f32_e32 v22, v22
	v_add_f32_e32 v26, 1.0, v26
	v_mul_f32_e32 v18, v18, v50
	v_exp_f32_e32 v18, v18
	v_mul_f32_e32 v43, v20, v23
	v_fmamk_f32 v20, v44, 0xbfb8aa3b, v49
	v_rcp_f32_e32 v26, v26
	v_fma_f32 v27, -v18, v18, 1.0
	v_sqrt_f32_e32 v27, v27
	v_mul_f32_e32 v42, v19, v22
	v_fmamk_f32 v22, v28, 0xbfb8aa3b, v48
	v_exp_f32_e32 v20, v20
	v_exp_f32_e32 v22, v22
	v_mul_f32_e32 v19, v26, v27
	v_mul_f32_e32 v11, v11, v19
	v_add_f32_e32 v19, 1.0, v20
	v_rcp_f32_e32 v19, v19
	v_add_f32_e32 v20, 1.0, v22
	v_fmamk_f32 v22, v45, 0xbfb8aa3b, v49
	v_exp_f32_e32 v22, v22
	v_mul_f32_e32 v19, v19, v50
	v_exp_f32_e32 v44, v19
	v_add_f32_e32 v19, 1.0, v22
	v_rcp_f32_e32 v19, v19
	v_exp_f32_e32 v24, v24
	v_fmamk_f32 v22, v29, 0xbfb8aa3b, v48
	v_mul_f32_e32 v19, v19, v50
	v_exp_f32_e32 v45, v19
	v_fmamk_f32 v19, v46, 0xbfb8aa3b, v49
	v_exp_f32_e32 v19, v19
	v_add_f32_e32 v24, 1.0, v24
	v_fma_f32 v25, -v41, v41, 1.0
	v_add_f32_e32 v19, 1.0, v19
	v_rcp_f32_e32 v19, v19
	v_exp_f32_e32 v22, v22
	v_rcp_f32_e32 v24, v24
	v_sqrt_f32_e32 v25, v25
	v_mul_f32_e32 v19, v19, v50
	v_exp_f32_e32 v46, v19
	v_fmamk_f32 v19, v47, 0xbfb8aa3b, v49
	v_add_f32_e32 v22, 1.0, v22
	v_exp_f32_e32 v19, v19
	v_mul_f32_e32 v52, v24, v25
	v_rcp_f32_e32 v24, v22
	v_fma_f32 v22, -v45, v45, 1.0
	v_sqrt_f32_e32 v25, v22
	v_fmamk_f32 v22, v30, 0xbfb8aa3b, v48
	v_exp_f32_e32 v22, v22
	v_add_f32_e32 v19, 1.0, v19
	v_rcp_f32_e32 v19, v19
	v_fma_f32 v27, -v46, v46, 1.0
	v_add_f32_e32 v22, 1.0, v22
	v_rcp_f32_e32 v26, v22
	v_fmamk_f32 v22, v31, 0xbfb8aa3b, v48
	v_mul_f32_e32 v19, v19, v50
	v_exp_f32_e32 v28, v22
	v_exp_f32_e32 v22, v19
	v_sqrt_f32_e32 v19, v27
	v_fma_f32 v23, -v44, v44, 1.0
	v_add_f32_e32 v27, 1.0, v28
	v_fma_f32 v28, -v22, v22, 1.0
	v_rcp_f32_e32 v27, v27
	v_sqrt_f32_e32 v28, v28
	v_rcp_f32_e32 v20, v20
	v_sqrt_f32_e32 v23, v23
	v_mul_f32_e32 v49, v26, v19
	v_mul_f32_e32 v19, v27, v28
	v_fmac_f32_e32 v7, 0, v17
	v_mul_f32_e32 v15, v15, v19
	v_mul_f32_e32 v19, v38, v7
	v_fmac_f32_e32 v19, v6, v21
	v_fmac_f32_e32 v3, 0, v16
	v_mul_f32_e32 v21, v37, v19
	v_mul_f32_e32 v47, v20, v23
	v_mul_f32_e32 v20, v53, v3
	v_fmac_f32_e32 v21, v5, v55
	v_fmac_f32_e32 v15, 0, v22
	v_mul_f32_e32 v48, v24, v25
	v_fmac_f32_e32 v20, v2, v35
	v_mul_f32_e32 v24, v36, v21
	v_fmac_f32_e32 v11, 0, v18
	v_mul_f32_e32 v2, v46, v15
	v_fmac_f32_e32 v24, v4, v54
	v_mul_f32_e32 v4, v41, v11
	v_fmac_f32_e32 v2, v14, v49
	v_fmac_f32_e32 v4, v10, v52
	v_mul_f32_e32 v5, v45, v2
	v_mul_f32_e32 v23, v51, v20
	v_mul_f32_e32 v6, v40, v4
	v_fmac_f32_e32 v5, v13, v48
	v_fmac_f32_e32 v23, v1, v34
	v_fmac_f32_e32 v6, v9, v43
	v_mul_f32_e32 v14, v22, v46
	v_mul_f32_e32 v9, v44, v5
	v_mul_f32_e32 v25, v33, v23
	v_mul_f32_e32 v13, v45, v14
	v_fmac_f32_e32 v9, v12, v47
	v_fmac_f32_e32 v25, v0, v32
	v_mul_f32_e32 v12, v44, v13
	ds_bpermute_b32 v0, v137, v9
	ds_bpermute_b32 v35, v137, v12
	v_mul_f32_e32 v28, v18, v41
	v_mul_f32_e32 v26, v16, v53
	v_mul_f32_e32 v27, v17, v38
	v_mul_f32_e32 v31, v40, v28
	v_mul_f32_e32 v10, v39, v6
	v_mul_f32_e32 v29, v51, v26
	v_mul_f32_e32 v30, v37, v27
	v_fmac_f32_e32 v10, v8, v42
	v_mul_f32_e32 v34, v39, v31
	v_mul_f32_e32 v32, v33, v29
	v_mul_f32_e32 v33, v36, v30
	s_waitcnt lgkmcnt(1)
	v_cndmask_b32_e64 v36, v0, v9, s[4:5]
	v_cndmask_b32_e64 v37, v9, v0, s[4:5]
	ds_bpermute_b32 v0, v137, v34
	ds_bpermute_b32 v40, v137, v10
	s_waitcnt lgkmcnt(2)
	v_cndmask_b32_e64 v8, v12, v35, s[4:5]
	v_fmac_f32_e32 v37, 0, v8
	ds_bpermute_b32 v8, v137, v33
	v_cndmask_b32_e64 v1, v35, v12, s[4:5]
	v_mul_f32_e32 v38, v12, v35
	v_fmac_f32_e32 v36, v1, v37
	s_waitcnt lgkmcnt(2)
	v_cndmask_b32_e64 v1, v0, v34, s[4:5]
	s_waitcnt lgkmcnt(1)
	v_cndmask_b32_e64 v39, v40, v10, s[4:5]
	v_cndmask_b32_e64 v0, v34, v0, s[4:5]
	v_cndmask_b32_e64 v40, v10, v40, s[4:5]
	ds_bpermute_b32 v44, v137, v24
	v_mul_f32_e32 v41, v38, v0
	v_fmac_f32_e32 v40, v0, v36
	v_mul_f32_e32 v42, v1, v41
	v_fmac_f32_e32 v39, v1, v40
	s_waitcnt lgkmcnt(1)
	v_cndmask_b32_e64 v0, v8, v33, s[4:5]
	v_cndmask_b32_e64 v1, v33, v8, s[4:5]
	ds_bpermute_b32 v8, v137, v32
	ds_bpermute_b32 v47, v137, v25
	s_waitcnt lgkmcnt(2)
	v_cndmask_b32_e64 v43, v44, v24, s[4:5]
	v_cndmask_b32_e64 v44, v24, v44, s[4:5]
	v_mul_f32_e32 v45, v1, v42
	v_fmac_f32_e32 v44, v1, v39
	v_mul_f32_e32 v46, v0, v45
	v_fmac_f32_e32 v43, v0, v44
	s_waitcnt lgkmcnt(1)
	v_cndmask_b32_e64 v0, v32, v8, s[4:5]
	s_waitcnt lgkmcnt(0)
	v_cndmask_b32_e64 v47, v25, v47, s[4:5]
	v_mul_f32_e32 v48, v0, v46
	v_fmac_f32_e32 v47, v0, v43
	s_and_saveexec_b64 s[12:13], s[4:5]
	v_mul_f32_e32 v0, v32, v48
	v_fma_f32 v1, v32, v47, v25
	ds_write_b64 v136, v[0:1] offset:6144
	s_or_b64 exec, exec, s[12:13]
	s_and_b64 vcc, exec, s[8:9]
	s_waitcnt lgkmcnt(0)
	s_barrier
	s_cbranch_vccnz .LBB0_293
	v_add3_u32 v49, v140, v91, s95
	v_mov_b32_e32 v8, 1.0
	v_mov_b32_e32 v1, 0
	s_mov_b32 s8, 7

.LBB0_331:
	v_mov_b32_e32 v178, v0
	v_mov_b32_e32 v181, v3
	v_mov_b64_e32 v[182:183], v[4:5]
	v_mov_b64_e32 v[184:185], v[6:7]
	v_mov_b64_e32 v[186:187], v[8:9]
	v_mov_b64_e32 v[188:189], v[10:11]
	v_mov_b64_e32 v[190:191], v[12:13]
	v_mov_b64_e32 v[192:193], v[14:15]
	v_mov_b64_e32 v[194:195], v[16:17]
	v_mov_b64_e32 v[196:197], v[18:19]
	v_mov_b64_e32 v[198:199], v[20:21]
	v_mov_b64_e32 v[200:201], v[22:23]
	v_mov_b64_e32 v[202:203], v[24:25]
	v_mov_b64_e32 v[204:205], v[26:27]
	v_mov_b64_e32 v[206:207], v[28:29]
	v_mov_b64_e32 v[208:209], v[30:31]
	v_mov_b64_e32 v[210:211], v[32:33]
	v_mov_b64_e32 v[212:213], v[34:35]
	v_mov_b64_e32 v[214:215], v[36:37]
	v_mov_b64_e32 v[216:217], v[38:39]
	v_mov_b64_e32 v[218:219], v[40:41]
	v_mov_b64_e32 v[220:221], v[42:43]
	v_mov_b64_e32 v[222:223], v[44:45]
	v_mov_b64_e32 v[238:239], v[46:47]
	s_setprio 1
	ds_read_b128 v[0:3], v148 offset:24576
	ds_read_b128 v[4:7], v148 offset:57344
	s_waitcnt lgkmcnt(1)
	v_mfma_f32_32x32x16_bf16 v[32:47], v[48:51], v[0:3], 0
	v_lshl_add_u64 v[126:127], s[36:37], 0, v[88:89]
	v_lshl_add_u64 v[128:129], s[40:41], 0, v[88:89]
	v_lshl_add_u64 v[130:131], s[42:43], 0, v[88:89]
	v_cndmask_b32_e64 v179, v191, 1.0, s[0:1]
	v_cndmask_b32_e64 v180, v188, 0, s[0:1]
	v_cndmask_b32_e64 v188, v220, v193, s[0:1]
	v_cndmask_b32_e64 v191, v195, v192, s[0:1]
	v_cndmask_b32_e64 v192, v238, v221, s[0:1]
	v_cndmask_b32_e64 v193, v222, v219, s[0:1]
	s_ashr_i32 s9, s8, 31
	s_waitcnt lgkmcnt(0)
	v_mfma_f32_32x32x16_bf16 v[16:31], v[48:51], v[4:7], 0
	v_lshlrev_b32_e32 v88, 2, v94
	v_cndmask_b32_e64 v195, v96, v239, s[0:1]
	v_cndmask_b32_e64 v219, v91, v223, s[0:1]
	v_fmac_f32_e32 v196, v210, v180
	v_mul_f32_e32 v210, v179, v210
	v_fmac_f32_e32 v209, v211, v180
	v_mul_f32_e32 v211, v179, v211
	v_fmac_f32_e32 v208, v212, v180
	v_mul_f32_e32 v212, v179, v212
	v_fmac_f32_e32 v207, v213, v180
	ds_read_b128 v[0:3], v150 offset:24576
	ds_read_b128 v[4:7], v150 offset:57344
	s_waitcnt lgkmcnt(1)
	v_mfma_f32_32x32x16_bf16 v[32:47], v[52:55], v[0:3], v[32:47]
	v_mul_f32_e32 v179, v179, v213
	v_fmac_f32_e32 v197, v198, v191
	v_mul_f32_e32 v180, v198, v188
	v_fmac_f32_e32 v206, v214, v191
	v_mul_f32_e32 v198, v214, v188
	v_fmac_f32_e32 v205, v215, v191
	v_mul_f32_e32 v213, v215, v188
	v_fmac_f32_e32 v204, v216, v191
	v_mul_f32_e32 v188, v216, v188
	v_fmac_f32_e32 v201, v190, v193
	s_waitcnt lgkmcnt(0)
	v_mfma_f32_32x32x16_bf16 v[16:31], v[52:55], v[4:7], v[16:31]
	v_mul_f32_e32 v216, v190, v192
	v_lshl_add_u64 v[190:191], s[22:23], 0, v[88:89]
	s_lshl_b64 s[4:5], s[8:9], 12
	v_fmac_f32_e32 v202, v218, v193
	v_mul_f32_e32 v215, v218, v192
	v_fmac_f32_e32 v185, v182, v219
	v_mul_f32_e32 v218, v182, v195
	v_lshl_add_u64 v[94:95], v[190:191], 0, s[4:5]
	v_lshlrev_b32_e32 v190, 14, v93
	v_mul_f32_e32 v182, v210, v178
	ds_read_b128 v[0:3], v145 offset:24576
	ds_read_b128 v[4:7], v145 offset:57344
	s_waitcnt lgkmcnt(1)
	v_mfma_f32_32x32x16_bf16 v[32:47], v[56:59], v[0:3], v[32:47]
	v_mov_b32_e32 v191, v89
	v_fmac_f32_e32 v196, v210, v181
	v_cvt_pk_bf16_f32 v182, v196, v182
	v_lshl_add_u64 v[96:97], v[94:95], 0, v[190:191]
	global_load_dword v172, v[130:131], off offset:128
	global_load_dword v173, v[126:127], off offset:128
	global_load_dword v174, v[128:129], off offset:128
	global_store_dword v[96:97], v182, off nt
	v_mul_f32_e32 v182, v211, v178
	v_or_b32_e32 v88, 0x1000, v190
	s_waitcnt lgkmcnt(0)
	v_mfma_f32_32x32x16_bf16 v[16:31], v[56:59], v[4:7], v[16:31]
	v_fmac_f32_e32 v199, v200, v193
	v_mul_f32_e32 v200, v200, v192
	v_fmac_f32_e32 v203, v217, v193
	v_mul_f32_e32 v214, v217, v192
	v_fmac_f32_e32 v209, v211, v181
	v_cvt_pk_bf16_f32 v182, v209, v182
	v_lshl_add_u64 v[192:193], v[94:95], 0, v[88:89]
	v_or_b32_e32 v98, 0x2000, v190
	v_mov_b32_e32 v99, v89
	global_store_dword v[192:193], v182, off nt
	ds_read_b128 v[0:3], v149 offset:24576
	ds_read_b128 v[4:7], v149 offset:57344
	s_waitcnt lgkmcnt(1)
	v_mfma_f32_32x32x16_bf16 v[32:47], v[60:63], v[0:3], v[32:47]
	v_mul_f32_e32 v182, v212, v178
	v_lshl_add_u64 v[192:193], v[94:95], 0, v[98:99]
	v_fmac_f32_e32 v207, v179, v181
	v_mul_f32_e32 v179, v179, v178
	v_or_b32_e32 v100, 0x3000, v190
	v_mov_b32_e32 v101, v89
	v_fmac_f32_e32 v208, v212, v181
	v_cvt_pk_bf16_f32 v182, v208, v182
	global_store_dword v[192:193], v182, off nt
	v_cvt_pk_bf16_f32 v179, v207, v179
	s_waitcnt lgkmcnt(0)
	v_mfma_f32_32x32x16_bf16 v[16:31], v[60:63], v[4:7], v[16:31]
	v_lshl_add_u64 v[192:193], v[94:95], 0, v[100:101]
	global_store_dword v[192:193], v179, off nt
	v_mul_f32_e32 v179, v180, v178
	v_or_b32_e32 v102, 0x8000, v190
	v_mov_b32_e32 v103, v89
	v_fmac_f32_e32 v197, v180, v181
	v_cvt_pk_bf16_f32 v179, v197, v179
	v_lshl_add_u64 v[192:193], v[94:95], 0, v[102:103]
	global_store_dword v[192:193], v179, off nt
	v_mul_f32_e32 v179, v198, v178
	ds_read_b128 v[0:3], v144 offset:24576
	ds_read_b128 v[4:7], v144 offset:57344
	s_waitcnt lgkmcnt(1)
	v_mfma_f32_32x32x16_bf16 v[32:47], v[64:67], v[0:3], v[32:47]
	v_or_b32_e32 v104, 0x9000, v190
	v_mov_b32_e32 v105, v89
	v_fmac_f32_e32 v206, v198, v181
	v_cvt_pk_bf16_f32 v179, v206, v179
	v_lshl_add_u64 v[192:193], v[94:95], 0, v[104:105]
	global_store_dword v[192:193], v179, off nt
	v_mul_f32_e32 v179, v213, v178
	v_or_b32_e32 v106, 0xa000, v190
	v_mov_b32_e32 v107, v89
	v_fmac_f32_e32 v205, v213, v181
	s_waitcnt lgkmcnt(0)
	v_mfma_f32_32x32x16_bf16 v[16:31], v[64:67], v[4:7], v[16:31]
	v_cvt_pk_bf16_f32 v179, v205, v179
	v_lshl_add_u64 v[192:193], v[94:95], 0, v[106:107]
	global_store_dword v[192:193], v179, off nt
	v_mul_f32_e32 v179, v188, v178
	v_or_b32_e32 v108, 0xb000, v190
	v_mov_b32_e32 v109, v89
	v_fmac_f32_e32 v204, v188, v181
	v_cvt_pk_bf16_f32 v179, v204, v179
	v_lshl_add_u64 v[192:193], v[94:95], 0, v[108:109]
	global_store_dword v[192:193], v179, off nt
	ds_read_b128 v[0:3], v147 offset:24576
	ds_read_b128 v[4:7], v147 offset:57344
	s_waitcnt lgkmcnt(1)
	v_mfma_f32_32x32x16_bf16 v[32:47], v[68:71], v[0:3], v[32:47]
	v_mul_f32_e32 v179, v200, v178
	v_or_b32_e32 v110, 0x10000, v190
	v_mov_b32_e32 v111, v89
	v_fmac_f32_e32 v199, v200, v181
	v_cvt_pk_bf16_f32 v179, v199, v179
	v_lshl_add_u64 v[192:193], v[94:95], 0, v[110:111]
	global_store_dword v[192:193], v179, off nt
	v_mul_f32_e32 v179, v214, v178
	v_or_b32_e32 v112, 0x11000, v190
	v_mov_b32_e32 v113, v89
	s_waitcnt lgkmcnt(0)
	v_mfma_f32_32x32x16_bf16 v[16:31], v[68:71], v[4:7], v[16:31]
	v_fmac_f32_e32 v203, v214, v181
	v_cvt_pk_bf16_f32 v179, v203, v179
	v_lshl_add_u64 v[192:193], v[94:95], 0, v[112:113]
	global_store_dword v[192:193], v179, off nt
	v_mul_f32_e32 v179, v215, v178
	v_or_b32_e32 v114, 0x12000, v190
	v_mov_b32_e32 v115, v89
	v_fmac_f32_e32 v202, v215, v181
	v_cvt_pk_bf16_f32 v179, v202, v179
	v_lshl_add_u64 v[192:193], v[94:95], 0, v[114:115]
	ds_read_b128 v[0:3], v143 offset:24576
	ds_read_b128 v[4:7], v143 offset:57344
	s_waitcnt lgkmcnt(1)
	v_mfma_f32_32x32x16_bf16 v[32:47], v[72:75], v[0:3], v[32:47]
	global_store_dword v[192:193], v179, off nt
	v_mul_f32_e32 v179, v216, v178
	v_or_b32_e32 v116, 0x13000, v190
	v_mov_b32_e32 v117, v89
	v_fmac_f32_e32 v186, v194, v219
	v_mul_f32_e32 v194, v194, v195
	v_fmac_f32_e32 v201, v216, v181
	v_cvt_pk_bf16_f32 v179, v201, v179
	v_lshl_add_u64 v[192:193], v[94:95], 0, v[116:117]
	global_store_dword v[192:193], v179, off nt
	s_waitcnt lgkmcnt(0)
	v_mfma_f32_32x32x16_bf16 v[16:31], v[72:75], v[4:7], v[16:31]
	v_fmac_f32_e32 v186, v194, v181
	v_mul_f32_e32 v179, v194, v178
	v_or_b32_e32 v118, 0x18000, v190
	v_mov_b32_e32 v119, v89
	v_fmac_f32_e32 v183, v187, v219
	v_mul_f32_e32 v217, v187, v195
	v_cvt_pk_bf16_f32 v179, v186, v179
	v_lshl_add_u64 v[186:187], v[94:95], 0, v[118:119]
	global_store_dword v[186:187], v179, off nt
	v_fmac_f32_e32 v183, v217, v181
	ds_read_b128 v[0:3], v146 offset:24576
	ds_read_b128 v[4:7], v146 offset:57344
	s_waitcnt lgkmcnt(1)
	v_mfma_f32_32x32x16_bf16 v[32:47], v[76:79], v[0:3], v[32:47]
	v_mul_f32_e32 v179, v217, v178
	v_or_b32_e32 v120, 0x19000, v190
	v_mov_b32_e32 v121, v89
	v_cvt_pk_bf16_f32 v179, v183, v179
	v_lshl_add_u64 v[182:183], v[94:95], 0, v[120:121]
	v_fmac_f32_e32 v189, v184, v219
	v_mul_f32_e32 v184, v184, v195
	s_lshl_b32 s6, s63, 11
	global_store_dword v[182:183], v179, off nt
	v_mul_f32_e32 v179, v218, v178
	s_waitcnt lgkmcnt(0)
	v_mfma_f32_32x32x16_bf16 v[16:31], v[76:79], v[4:7], v[16:31]
	v_or_b32_e32 v122, 0x1a000, v190
	v_mov_b32_e32 v123, v89
	s_or_b32 s6, s6, s70
	v_fmac_f32_e32 v185, v218, v181
	v_cvt_pk_bf16_f32 v179, v185, v179
	v_lshl_add_u64 v[182:183], v[94:95], 0, v[122:123]
	v_mul_f32_e32 v178, v184, v178
	v_or_b32_e32 v124, 0x1b000, v190
	v_mov_b32_e32 v125, v89
	v_lshl_add_u32 v142, v92, 3, 16
	v_mfma_f32_32x32x16_bf16 v[0:15], v[56:59], v[80:83], 0
	v_cmp_gt_i32_e64 s[4:5], 32, v92
	v_add_u32_e32 v92, s6, v92
	global_store_dword v[182:183], v179, off nt
	v_fmac_f32_e32 v189, v184, v181
	v_cvt_pk_bf16_f32 v180, v189, v178
	v_lshl_add_u64 v[178:179], v[94:95], 0, v[124:125]
	global_store_dword v[178:179], v180, off nt
	v_mfma_f32_32x32x16_bf16 v[0:15], v[60:63], v[84:87], v[0:15]
	s_setprio 0
	s_and_saveexec_b64 s[6:7], s[4:5]
	s_cbranch_execz .LBB0_333
	ds_read2_b64 v[178:181], v142 offset1:32
	ds_read2_b64 v[182:185], v142 offset0:64 offset1:96
	ds_read2_b64 v[186:189], v142 offset0:128 offset1:160
	ds_read2_b64 v[190:193], v142 offset0:192 offset1:224
	v_ashrrev_i32_e32 v93, 31, v92
	s_waitcnt lgkmcnt(3)
	v_fma_f32 v194, 0, v178, v179
	v_pk_mul_f32 v[178:179], v[178:179], v[180:181]
	v_fma_f32 v180, v180, v194, v181
	s_waitcnt lgkmcnt(2)
	v_fma_f32 v180, v182, v180, v183
	v_fma_f32 v180, v184, v180, v185
	s_waitcnt lgkmcnt(1)
	v_fma_f32 v181, v186, v180, v187
	v_mov_b32_e32 v180, v178
	v_mov_b32_e32 v194, v182
	v_mov_b32_e32 v195, v188
	v_pk_mul_f32 v[178:179], v[178:179], v[182:183]
	v_pk_fma_f32 v[180:181], v[180:181], v[194:195], v[188:189]
	v_pk_mul_f32 v[178:179], v[178:179], v[184:185]
	s_waitcnt lgkmcnt(0)
	v_mov_b32_e32 v187, v190
	v_mov_b32_e32 v179, v181
	v_pk_mul_f32 v[180:181], v[178:179], v[186:187]
	v_pk_fma_f32 v[178:179], v[178:179], v[186:187], v[190:191]
	v_pk_mul_f32 v[180:181], v[180:181], v[188:189]
	v_mov_b32_e32 v182, v190
	v_mov_b32_e32 v178, v180
	v_mov_b32_e32 v183, v192
	v_pk_mul_f32 v[180:181], v[180:181], v[190:191]
	v_pk_fma_f32 v[178:179], v[178:179], v[182:183], v[192:193]
	v_pk_mul_f32 v[180:181], v[180:181], v[192:193]
	s_nop 0
	v_mov_b32_e32 v181, v179
	v_lshl_add_u64 v[178:179], v[92:93], 3, s[24:25]
	global_store_dwordx2 v[178:179], v[180:181], off
.LBB0_333:
	s_or_b64 exec, exec, s[6:7]
	s_waitcnt vmcnt(16)
	ds_read_b32 v251, v167 offset:128
	v_mul_f32_e32 v151, 0xbfb8aa3b, v173
	v_mul_f32_e32 v93, 0xbfb8aa3b, v174
	v_fmamk_f32 v32, v32, 0xbfb8aa3b, v151
	v_fmamk_f32 v34, v34, 0xbfb8aa3b, v151
	v_fmamk_f32 v33, v33, 0xbfb8aa3b, v151
	v_fmamk_f32 v35, v35, 0xbfb8aa3b, v151
	v_fmamk_f32 v16, v16, 0xbfb8aa3b, v93
	v_fmamk_f32 v17, v17, 0xbfb8aa3b, v93
	v_exp_f32_e32 v32, v32
	v_exp_f32_e32 v34, v34
	v_exp_f32_e32 v33, v33
	v_exp_f32_e32 v161, v35
	v_exp_f32_e32 v91, v16
	v_exp_f32_e32 v152, v17
	v_add_f32_e32 v32, 1.0, v32
	v_add_f32_e32 v162, 1.0, v34
	v_add_f32_e32 v33, 1.0, v33
	v_rcp_f32_e32 v163, v32
	v_rcp_f32_e32 v165, v33
	v_add_f32_e32 v91, 1.0, v91
	v_rcp_f32_e32 v164, v91
	v_add_f32_e32 v152, 1.0, v152
	v_rcp_f32_e32 v166, v152
	v_fmamk_f32 v18, v18, 0xbfb8aa3b, v93
	v_exp_f32_e32 v18, v18
	v_fmamk_f32 v20, v20, 0xbfb8aa3b, v93
	v_add_f32_e32 v18, 1.0, v18
	v_exp_f32_e32 v20, v20
	v_fmamk_f32 v19, v19, 0xbfb8aa3b, v93
	v_exp_f32_e32 v19, v19
	v_fmamk_f32 v21, v21, 0xbfb8aa3b, v93
	s_waitcnt lgkmcnt(0)
	v_mul_f32_e32 v33, 0x3fb8aa3b, v251
	v_mul_f32_e32 v16, v163, v33
	v_exp_f32_e32 v32, v16
	v_mul_f32_e32 v17, v165, v33
	v_exp_f32_e32 v34, v17
	v_rcp_f32_e32 v16, v162
	v_rcp_f32_e32 v17, v18
	v_fma_f32 v18, -v32, v32, 1.0
	v_sqrt_f32_e32 v18, v18
	v_mul_f32_e32 v16, v16, v33
	v_add_f32_e32 v19, 1.0, v19
	v_mul_f32_e32 v18, v164, v18
	v_mul_f32_e32 v18, v0, v18
	v_exp_f32_e32 v0, v16
	v_add_f32_e32 v16, 1.0, v161
	v_rcp_f32_e32 v16, v16
	v_rcp_f32_e32 v19, v19
	v_fma_f32 v91, -v0, v0, 1.0
	v_sqrt_f32_e32 v91, v91
	v_mul_f32_e32 v16, v16, v33
	v_exp_f32_e32 v152, v16
	v_fmamk_f32 v16, v36, 0xbfb8aa3b, v151
	v_exp_f32_e32 v16, v16
	v_mul_f32_e32 v91, v17, v91
	v_add_f32_e32 v17, 1.0, v20
	v_fma_f32 v36, -v152, v152, 1.0
	v_add_f32_e32 v16, 1.0, v16
	v_rcp_f32_e32 v16, v16
	v_sqrt_f32_e32 v36, v36
	v_rcp_f32_e32 v17, v17
	v_mul_f32_e32 v16, v16, v33
	v_exp_f32_e32 v20, v16
	v_fmamk_f32 v16, v37, 0xbfb8aa3b, v151
	v_exp_f32_e32 v16, v16
	v_mul_f32_e32 v36, v19, v36
	v_fma_f32 v19, -v20, v20, 1.0
	v_sqrt_f32_e32 v19, v19
	v_add_f32_e32 v16, 1.0, v16
	v_rcp_f32_e32 v16, v16
	v_exp_f32_e32 v21, v21
	v_mul_f32_e32 v17, v17, v19
	v_mul_f32_e32 v19, v4, v17
	v_mul_f32_e32 v16, v16, v33
	v_exp_f32_e32 v37, v16
	v_fmamk_f32 v16, v38, 0xbfb8aa3b, v151
	v_exp_f32_e32 v16, v16
	v_add_f32_e32 v4, 1.0, v21
	v_fmamk_f32 v21, v22, 0xbfb8aa3b, v93
	v_add_f32_e32 v16, 1.0, v16
	v_rcp_f32_e32 v16, v16
	v_fma_f32 v17, -v37, v37, 1.0
	v_exp_f32_e32 v21, v21
	v_rcp_f32_e32 v4, v4
	v_mul_f32_e32 v16, v16, v33
	v_sqrt_f32_e32 v17, v17
	v_exp_f32_e32 v38, v16
	v_add_f32_e32 v16, 1.0, v21
	v_fmamk_f32 v21, v39, 0xbfb8aa3b, v151
	v_mul_f32_e32 v4, v4, v17
	v_fma_f32 v17, -v38, v38, 1.0
	v_rcp_f32_e32 v16, v16
	v_sqrt_f32_e32 v17, v17
	v_exp_f32_e32 v21, v21
	v_fmamk_f32 v22, v23, 0xbfb8aa3b, v93
	v_mul_f32_e32 v23, v16, v17
	v_add_f32_e32 v16, 1.0, v21
	v_rcp_f32_e32 v16, v16
	v_fmamk_f32 v21, v40, 0xbfb8aa3b, v151
	v_exp_f32_e32 v21, v21
	v_mul_f32_e32 v16, v16, v33
	v_exp_f32_e32 v39, v16
	v_add_f32_e32 v16, 1.0, v21
	v_rcp_f32_e32 v16, v16
	v_exp_f32_e32 v22, v22
	v_fmamk_f32 v21, v24, 0xbfb8aa3b, v93
	v_mul_f32_e32 v16, v16, v33
	v_add_f32_e32 v17, 1.0, v22
	v_fma_f32 v22, -v39, v39, 1.0
	v_sqrt_f32_e32 v24, v22
	v_exp_f32_e32 v22, v16
	v_fmamk_f32 v16, v41, 0xbfb8aa3b, v151
	v_exp_f32_e32 v16, v16
	v_exp_f32_e32 v21, v21
	v_fma_f32 v40, -v22, v22, 1.0
	v_rcp_f32_e32 v17, v17
	v_add_f32_e32 v16, 1.0, v16
	v_rcp_f32_e32 v16, v16
	v_add_f32_e32 v21, 1.0, v21
	v_rcp_f32_e32 v21, v21
	v_sqrt_f32_e32 v40, v40
	v_mul_f32_e32 v16, v16, v33
	v_mul_f32_e32 v24, v17, v24
	v_mul_f32_e32 v17, v21, v40
	v_exp_f32_e32 v40, v16
	v_fmamk_f32 v16, v42, 0xbfb8aa3b, v151
	v_fmamk_f32 v25, v25, 0xbfb8aa3b, v93
	v_exp_f32_e32 v16, v16
	v_exp_f32_e32 v25, v25
	v_fma_f32 v35, -v34, v34, 1.0
	v_sqrt_f32_e32 v35, v35
	v_add_f32_e32 v16, 1.0, v16
	v_add_f32_e32 v21, 1.0, v25
	v_rcp_f32_e32 v16, v16
	v_rcp_f32_e32 v25, v21
	v_fma_f32 v21, -v40, v40, 1.0
	v_sqrt_f32_e32 v41, v21
	v_fmamk_f32 v21, v26, 0xbfb8aa3b, v93
	v_mul_f32_e32 v16, v16, v33
	v_exp_f32_e32 v26, v21
	v_mul_f32_e32 v21, v8, v17
	v_mul_f32_e32 v8, v25, v41
	v_exp_f32_e32 v41, v16
	v_fmamk_f32 v16, v43, 0xbfb8aa3b, v151
	v_exp_f32_e32 v16, v16
	v_add_f32_e32 v17, 1.0, v26
	v_fma_f32 v25, -v41, v41, 1.0
	v_fmamk_f32 v26, v27, 0xbfb8aa3b, v93
	v_add_f32_e32 v16, 1.0, v16
	v_rcp_f32_e32 v16, v16
	v_rcp_f32_e32 v17, v17
	v_sqrt_f32_e32 v25, v25
	v_mul_f32_e32 v16, v16, v33
	v_exp_f32_e32 v26, v26
	v_exp_f32_e32 v153, v16
	v_mul_f32_e32 v154, v17, v25
	v_fmamk_f32 v25, v44, 0xbfb8aa3b, v151
	v_add_f32_e32 v16, 1.0, v26
	v_fmamk_f32 v26, v28, 0xbfb8aa3b, v93
	v_fma_f32 v17, -v153, v153, 1.0
	v_exp_f32_e32 v25, v25
	v_rcp_f32_e32 v16, v16
	v_sqrt_f32_e32 v17, v17
	v_exp_f32_e32 v26, v26
	v_add_f32_e32 v25, 1.0, v25
	v_rcp_f32_e32 v25, v25
	v_mul_f32_e32 v155, v16, v17
	v_add_f32_e32 v16, 1.0, v26
	v_fmamk_f32 v26, v29, 0xbfb8aa3b, v93
	v_exp_f32_e32 v26, v26
	v_rcp_f32_e32 v17, v16
	v_mul_f32_e32 v16, v25, v33
	v_fmamk_f32 v25, v45, 0xbfb8aa3b, v151
	v_exp_f32_e32 v25, v25
	v_add_f32_e32 v26, 1.0, v26
	v_rcp_f32_e32 v42, v26
	v_fmamk_f32 v26, v46, 0xbfb8aa3b, v151
	v_exp_f32_e32 v26, v26
	v_add_f32_e32 v25, 1.0, v25
	v_rcp_f32_e32 v25, v25
	v_fmamk_f32 v27, v30, 0xbfb8aa3b, v93
	v_exp_f32_e32 v27, v27
	v_add_f32_e32 v26, 1.0, v26
	v_rcp_f32_e32 v26, v26
	v_mul_f32_e32 v25, v25, v33
	v_exp_f32_e32 v43, v25
	v_add_f32_e32 v25, 1.0, v27
	v_rcp_f32_e32 v44, v25
	v_mul_f32_e32 v25, v26, v33
	v_fmamk_f32 v26, v47, 0xbfb8aa3b, v151
	v_exp_f32_e32 v26, v26
	v_fmamk_f32 v27, v31, 0xbfb8aa3b, v93
	v_exp_f32_e32 v27, v27
	v_add_f32_e32 v26, 1.0, v26
	v_rcp_f32_e32 v26, v26
	v_exp_f32_e32 v16, v16
	v_fmac_f32_e32 v18, 0, v32
	v_mul_f32_e32 v35, v166, v35
	v_exp_f32_e32 v45, v25
	v_add_f32_e32 v25, 1.0, v27
	v_mul_f32_e32 v31, v34, v18
	v_rcp_f32_e32 v46, v25
	v_mul_f32_e32 v25, v26, v33
	v_fmac_f32_e32 v31, v1, v35
	v_mul_f32_e32 v33, v32, v34
	v_fmac_f32_e32 v19, 0, v20
	v_mul_f32_e32 v30, v0, v31
	v_mul_f32_e32 v34, v0, v33
	v_mul_f32_e32 v28, v37, v19
	v_fma_f32 v0, -v16, v16, 1.0
	v_fmac_f32_e32 v28, v5, v4
	v_sqrt_f32_e32 v1, v0
	v_mul_f32_e32 v27, v38, v28
	v_fmac_f32_e32 v30, v2, v91
	v_fmac_f32_e32 v27, v6, v23
	v_fma_f32 v2, -v43, v43, 1.0
	v_mul_f32_e32 v26, v39, v27
	v_mov_b32_e32 v0, v89
	v_sqrt_f32_e32 v2, v2
	v_fmac_f32_e32 v26, v7, v24
	v_pk_mul_f32 v[6:7], v[16:17], v[0:1]
	v_mul_f32_e32 v29, v152, v30
	v_fmac_f32_e32 v6, v12, v7
	v_fmac_f32_e32 v29, v3, v36
	v_mov_b32_e32 v3, v6
	v_pk_mul_f32 v[4:5], v[42:43], v[2:3]
	v_fma_f32 v0, -v45, v45, 1.0
	v_exp_f32_e32 v47, v25
	v_fmac_f32_e32 v5, v13, v4
	v_sqrt_f32_e32 v4, v0
	v_fmac_f32_e32 v21, 0, v22
	v_mul_f32_e32 v25, v40, v21
	v_fmac_f32_e32 v25, v9, v8
	v_pk_mul_f32 v[8:9], v[44:45], v[4:5]
	v_fma_f32 v0, -v47, v47, 1.0
	v_fmac_f32_e32 v9, v14, v8
	v_sqrt_f32_e32 v8, v0
	ds_bpermute_b32 v0, v140, v29
	v_mul_f32_e32 v24, v41, v25
	v_mul_f32_e32 v35, v152, v34
	v_mul_f32_e32 v36, v20, v37
	v_fmac_f32_e32 v24, v10, v154
	v_mul_f32_e32 v37, v38, v36
	v_mul_f32_e32 v23, v153, v24
	ds_bpermute_b32 v13, v140, v35
	v_mul_f32_e32 v38, v39, v37
	v_fmac_f32_e32 v23, v11, v155
	v_pk_mul_f32 v[10:11], v[46:47], v[8:9]
	s_waitcnt lgkmcnt(1)
	v_cndmask_b32_e64 v14, v29, v0, s[0:1]
	v_fmac_f32_e32 v11, v15, v10
	v_cndmask_b32_e64 v10, v0, v29, s[0:1]
	ds_bpermute_b32 v0, v140, v38
	ds_bpermute_b32 v3, v140, v26
	v_mul_f32_e32 v39, v22, v40
	v_mul_f32_e32 v40, v41, v39
	s_waitcnt lgkmcnt(2)
	v_cndmask_b32_e64 v1, v13, v35, s[0:1]
	v_mul_f32_e32 v12, v153, v40
	v_mul_f32_e32 v7, v16, v43
	v_cndmask_b32_e64 v2, v35, v13, s[0:1]
	v_fmac_f32_e32 v10, 0, v1
	v_mul_f32_e32 v4, v45, v7
	v_mul_f32_e32 v15, v35, v13
	v_fmac_f32_e32 v14, v2, v10
	s_waitcnt lgkmcnt(1)
	v_cndmask_b32_e64 v1, v0, v38, s[0:1]
	s_waitcnt lgkmcnt(0)
	v_cndmask_b32_e64 v17, v3, v26, s[0:1]
	v_cndmask_b32_e64 v41, v26, v3, s[0:1]
	ds_bpermute_b32 v2, v140, v12
	ds_bpermute_b32 v3, v140, v23
	v_mul_f32_e32 v8, v47, v4
	v_cndmask_b32_e64 v0, v38, v0, s[0:1]
	v_mul_f32_e32 v42, v15, v1
	v_fmac_f32_e32 v17, v1, v14
	v_mul_f32_e32 v43, v0, v42
	v_fmac_f32_e32 v41, v0, v17
	ds_bpermute_b32 v1, v140, v8
	ds_bpermute_b32 v0, v140, v11
	s_waitcnt lgkmcnt(3)
	v_cndmask_b32_e64 v47, v2, v12, s[0:1]
	s_waitcnt lgkmcnt(2)
	v_cndmask_b32_e64 v44, v3, v23, s[0:1]
	v_cndmask_b32_e64 v2, v12, v2, s[0:1]
	v_cndmask_b32_e64 v45, v23, v3, s[0:1]
	v_mul_f32_e32 v46, v47, v43
	v_fmac_f32_e32 v44, v47, v41
	v_mul_f32_e32 v47, v2, v46
	v_fmac_f32_e32 v45, v2, v44
	s_waitcnt lgkmcnt(1)
	v_cndmask_b32_e64 v2, v1, v8, s[0:1]
	s_waitcnt lgkmcnt(0)
	v_cndmask_b32_e64 v91, v0, v11, s[0:1]
	v_mul_f32_e32 v93, v2, v47
	v_fmac_f32_e32 v91, v2, v45
	s_and_saveexec_b64 s[6:7], s[0:1]
	v_mul_f32_e32 v3, v91, v1
	v_mul_f32_e32 v2, v93, v1
	v_add_f32_e32 v3, v3, v0
	ds_write_b64 v139, v[2:3] offset:2048
	s_or_b64 exec, exec, s[6:7]
	v_cndmask_b32_e64 v0, 0, 1, s[12:13]
	v_cmp_ne_u32_e64 s[6:7], 1, v0
	s_andn2_b64 vcc, exec, s[12:13]
	s_waitcnt lgkmcnt(0)
	s_barrier
	s_cbranch_vccnz .LBB0_340
	s_cmp_lt_u32 s62, 8
	s_cbranch_scc1 .LBB0_341
	s_add_i32 s9, 16, 0x800
	s_and_b32 s8, s62, 0x7ffffff8
	v_add3_u32 v151, v141, v138, s9
	v_mov_b32_e32 v0, 1.0
	v_mov_b32_e32 v3, 0
	s_mov_b32 s9, 0

.LBB0_344:
	v_mov_b32_e32 v178, v0
	v_mov_b32_e32 v181, v3
	v_mov_b64_e32 v[182:183], v[4:5]
	v_mov_b64_e32 v[184:185], v[6:7]
	v_mov_b64_e32 v[186:187], v[8:9]
	v_mov_b64_e32 v[188:189], v[10:11]
	v_mov_b64_e32 v[190:191], v[12:13]
	v_mov_b64_e32 v[192:193], v[14:15]
	v_mov_b64_e32 v[194:195], v[16:17]
	v_mov_b64_e32 v[196:197], v[18:19]
	v_mov_b64_e32 v[198:199], v[20:21]
	v_mov_b64_e32 v[200:201], v[22:23]
	v_mov_b64_e32 v[202:203], v[24:25]
	v_mov_b64_e32 v[204:205], v[26:27]
	v_mov_b64_e32 v[206:207], v[28:29]
	v_mov_b64_e32 v[208:209], v[30:31]
	v_mov_b64_e32 v[210:211], v[32:33]
	v_mov_b64_e32 v[212:213], v[34:35]
	v_mov_b64_e32 v[214:215], v[36:37]
	v_mov_b64_e32 v[216:217], v[38:39]
	v_mov_b64_e32 v[218:219], v[40:41]
	v_mov_b64_e32 v[220:221], v[42:43]
	v_mov_b64_e32 v[222:223], v[44:45]
	v_mov_b64_e32 v[238:239], v[46:47]
	s_setprio 1
	ds_read_b128 v[0:3], v148 offset:32768
	ds_read_b128 v[4:7], v150 offset:32768
	v_add_u32_e32 v8, 0x8000, v150
	s_waitcnt lgkmcnt(1)
	v_mfma_f32_32x32x16_bf16 v[16:31], v[48:51], v[0:3], 0
	v_cndmask_b32_e64 v179, v191, 1.0, s[0:1]
	v_cndmask_b32_e64 v180, v188, 0, s[0:1]
	v_cndmask_b32_e64 v188, v220, v193, s[0:1]
	v_cndmask_b32_e64 v191, v195, v192, s[0:1]
	v_cndmask_b32_e64 v192, v238, v221, s[0:1]
	v_cndmask_b32_e64 v193, v222, v219, s[0:1]
	v_cndmask_b32_e64 v195, v93, v239, s[0:1]
	v_add_u32_e32 v0, 0x8000, v148
	ds_read_b128 v[0:3], v0 offset:32768
	ds_read_b128 v[8:11], v8 offset:32768
	s_waitcnt lgkmcnt(1)
	v_mfma_f32_32x32x16_bf16 v[32:47], v[48:51], v[0:3], 0
	v_cndmask_b32_e64 v219, v91, v223, s[0:1]
	v_fmac_f32_e32 v196, v210, v180
	v_mul_f32_e32 v210, v179, v210
	v_fmac_f32_e32 v209, v211, v180
	v_mul_f32_e32 v211, v179, v211
	v_fmac_f32_e32 v208, v212, v180
	v_mul_f32_e32 v212, v179, v212
	v_mfma_f32_32x32x16_bf16 v[16:31], v[52:55], v[4:7], v[16:31]
	v_fmac_f32_e32 v207, v213, v180
	v_mul_f32_e32 v179, v179, v213
	v_fmac_f32_e32 v205, v215, v191
	v_mul_f32_e32 v213, v215, v188
	v_fmac_f32_e32 v202, v218, v193
	v_mul_f32_e32 v215, v218, v192
	v_fmac_f32_e32 v187, v182, v219
	ds_read_b128 v[0:3], v145 offset:32768
	ds_read_b128 v[4:7], v149 offset:32768
	s_waitcnt lgkmcnt(2)
	v_mfma_f32_32x32x16_bf16 v[32:47], v[52:55], v[8:11], v[32:47]
	v_mul_f32_e32 v218, v182, v195
	v_mul_f32_e32 v182, v210, v178
	v_fmac_f32_e32 v196, v210, v181
	v_cvt_pk_bf16_f32 v182, v196, v182
	v_fmac_f32_e32 v197, v198, v191
	v_mul_f32_e32 v180, v198, v188
	v_fmac_f32_e32 v206, v214, v191
	v_add_u32_e32 v8, 0x8000, v149
	ds_read_b128 v[8:11], v8 offset:32768
	s_waitcnt lgkmcnt(2)
	v_mfma_f32_32x32x16_bf16 v[16:31], v[56:59], v[0:3], v[16:31]
	v_mul_f32_e32 v198, v214, v188
	v_fmac_f32_e32 v204, v216, v191
	v_mul_f32_e32 v188, v216, v188
	v_fmac_f32_e32 v201, v190, v193
	v_mul_f32_e32 v216, v190, v192
	v_lshl_add_u64 v[190:191], v[94:95], 0, s[38:39]
	global_load_dword v172, v[130:131], off offset:256
	v_add_u32_e32 v0, 0x8000, v145
	ds_read_b128 v[0:3], v0 offset:32768
	s_waitcnt lgkmcnt(0)
	v_mfma_f32_32x32x16_bf16 v[32:47], v[56:59], v[0:3], v[32:47]
	global_load_dword v173, v[126:127], off offset:256
	global_load_dword v174, v[128:129], off offset:256
	global_store_dword v[96:97], v182, off offset:128 nt
	v_mul_f32_e32 v182, v211, v178
	v_fmac_f32_e32 v199, v200, v193
	v_mul_f32_e32 v200, v200, v192
	v_fmac_f32_e32 v203, v217, v193
	v_mfma_f32_32x32x16_bf16 v[16:31], v[60:63], v[4:7], v[16:31]
	v_mul_f32_e32 v214, v217, v192
	v_fmac_f32_e32 v209, v211, v181
	v_cvt_pk_bf16_f32 v182, v209, v182
	v_lshl_add_u64 v[192:193], v[190:191], 0, v[88:89]
	global_store_dword v[192:193], v182, off nt
	v_mul_f32_e32 v182, v212, v178
	v_lshl_add_u64 v[192:193], v[190:191], 0, v[98:99]
	ds_read_b128 v[0:3], v144 offset:32768
	ds_read_b128 v[4:7], v147 offset:32768
	v_mfma_f32_32x32x16_bf16 v[32:47], v[60:63], v[8:11], v[32:47]
	v_fmac_f32_e32 v207, v179, v181
	v_mul_f32_e32 v179, v179, v178
	v_fmac_f32_e32 v208, v212, v181
	v_cvt_pk_bf16_f32 v182, v208, v182
	global_store_dword v[192:193], v182, off nt
	v_cvt_pk_bf16_f32 v179, v207, v179
	v_lshl_add_u64 v[192:193], v[190:191], 0, v[100:101]
	v_add_u32_e32 v8, 0x8000, v147
	ds_read_b128 v[8:11], v8 offset:32768
	s_waitcnt lgkmcnt(2)
	v_mfma_f32_32x32x16_bf16 v[16:31], v[64:67], v[0:3], v[16:31]
	global_store_dword v[192:193], v179, off nt
	v_mul_f32_e32 v179, v180, v178
	v_fmac_f32_e32 v197, v180, v181
	v_cvt_pk_bf16_f32 v179, v197, v179
	v_lshl_add_u64 v[192:193], v[190:191], 0, v[102:103]
	global_store_dword v[192:193], v179, off nt
	v_mul_f32_e32 v179, v198, v178
	v_add_u32_e32 v0, 0x8000, v144
	ds_read_b128 v[0:3], v0 offset:32768
	s_waitcnt lgkmcnt(0)
	v_mfma_f32_32x32x16_bf16 v[32:47], v[64:67], v[0:3], v[32:47]
	v_fmac_f32_e32 v206, v198, v181
	v_cvt_pk_bf16_f32 v179, v206, v179
	v_lshl_add_u64 v[192:193], v[190:191], 0, v[104:105]
	global_store_dword v[192:193], v179, off nt
	v_mul_f32_e32 v179, v213, v178
	v_fmac_f32_e32 v205, v213, v181
	v_cvt_pk_bf16_f32 v179, v205, v179
	v_mfma_f32_32x32x16_bf16 v[16:31], v[68:71], v[4:7], v[16:31]
	v_lshl_add_u64 v[192:193], v[190:191], 0, v[106:107]
	global_store_dword v[192:193], v179, off nt
	v_mul_f32_e32 v179, v188, v178
	v_fmac_f32_e32 v204, v188, v181
	v_cvt_pk_bf16_f32 v179, v204, v179
	v_lshl_add_u64 v[192:193], v[190:191], 0, v[108:109]
	global_store_dword v[192:193], v179, off nt
	ds_read_b128 v[0:3], v143 offset:32768
	ds_read_b128 v[4:7], v146 offset:32768
	v_mfma_f32_32x32x16_bf16 v[32:47], v[68:71], v[8:11], v[32:47]
	v_mul_f32_e32 v179, v200, v178
	v_fmac_f32_e32 v199, v200, v181
	v_cvt_pk_bf16_f32 v179, v199, v179
	v_lshl_add_u64 v[192:193], v[190:191], 0, v[110:111]
	global_store_dword v[192:193], v179, off nt
	v_mul_f32_e32 v179, v214, v178
	v_fmac_f32_e32 v203, v214, v181
	v_add_u32_e32 v8, 0x8000, v146
	ds_read_b128 v[8:11], v8 offset:32768
	s_waitcnt lgkmcnt(2)
	v_mfma_f32_32x32x16_bf16 v[16:31], v[72:75], v[0:3], v[16:31]
	v_cvt_pk_bf16_f32 v179, v203, v179
	v_lshl_add_u64 v[192:193], v[190:191], 0, v[112:113]
	global_store_dword v[192:193], v179, off nt
	v_mul_f32_e32 v179, v215, v178
	v_fmac_f32_e32 v202, v215, v181
	v_cvt_pk_bf16_f32 v179, v202, v179
	v_lshl_add_u64 v[192:193], v[190:191], 0, v[114:115]
	v_add_u32_e32 v0, 0x8000, v143
	ds_read_b128 v[0:3], v0 offset:32768
	s_waitcnt lgkmcnt(0)
	v_mfma_f32_32x32x16_bf16 v[32:47], v[72:75], v[0:3], v[32:47]
	global_store_dword v[192:193], v179, off nt
	v_mul_f32_e32 v179, v216, v178
	v_fmac_f32_e32 v184, v194, v219
	v_mul_f32_e32 v194, v194, v195
	v_fmac_f32_e32 v201, v216, v181
	v_cvt_pk_bf16_f32 v179, v201, v179
	v_lshl_add_u64 v[192:193], v[190:191], 0, v[116:117]
	v_mfma_f32_32x32x16_bf16 v[16:31], v[76:79], v[4:7], v[16:31]
	global_store_dword v[192:193], v179, off nt
	v_fmac_f32_e32 v184, v194, v181
	v_mul_f32_e32 v179, v194, v178
	v_fmac_f32_e32 v183, v185, v219
	v_mul_f32_e32 v217, v185, v195
	v_cvt_pk_bf16_f32 v179, v184, v179
	v_lshl_add_u64 v[184:185], v[190:191], 0, v[118:119]
	v_mfma_f32_32x32x16_bf16 v[32:47], v[76:79], v[8:11], v[32:47]
	global_store_dword v[184:185], v179, off nt
	v_fmac_f32_e32 v183, v217, v181
	v_mul_f32_e32 v179, v217, v178
	v_cvt_pk_bf16_f32 v179, v183, v179
	v_lshl_add_u64 v[182:183], v[190:191], 0, v[120:121]
	v_fmac_f32_e32 v189, v186, v219
	v_mul_f32_e32 v186, v186, v195
	v_mfma_f32_32x32x16_bf16 v[0:15], v[64:67], v[80:83], 0
	global_store_dword v[182:183], v179, off nt
	v_mul_f32_e32 v179, v218, v178
	v_fmac_f32_e32 v187, v218, v181
	v_cvt_pk_bf16_f32 v179, v187, v179
	v_lshl_add_u64 v[182:183], v[190:191], 0, v[122:123]
	v_mul_f32_e32 v178, v186, v178
	global_store_dword v[182:183], v179, off nt
	v_mfma_f32_32x32x16_bf16 v[0:15], v[68:71], v[84:87], v[0:15]
	v_fmac_f32_e32 v189, v186, v181
	v_cvt_pk_bf16_f32 v180, v189, v178
	v_lshl_add_u64 v[178:179], v[190:191], 0, v[124:125]
	global_store_dword v[178:179], v180, off nt
	s_setprio 0
	s_and_saveexec_b64 s[8:9], s[4:5]
	s_cbranch_execz .LBB0_346
	v_add_u32_e32 v190, 0x800, v142
	ds_read2_b64 v[178:181], v190 offset1:32
	ds_read2_b64 v[182:185], v190 offset0:64 offset1:96
	ds_read2_b64 v[186:189], v190 offset0:128 offset1:160
	ds_read2_b64 v[190:193], v190 offset0:192 offset1:224
	s_waitcnt lgkmcnt(3)
	v_fma_f32 v194, 0, v178, v179
	v_pk_mul_f32 v[178:179], v[178:179], v[180:181]
	v_fma_f32 v180, v180, v194, v181
	s_waitcnt lgkmcnt(2)
	v_fma_f32 v180, v182, v180, v183
	v_fma_f32 v180, v184, v180, v185
	s_waitcnt lgkmcnt(1)
	v_fma_f32 v181, v186, v180, v187
	v_mov_b32_e32 v180, v178
	v_mov_b32_e32 v194, v182
	v_mov_b32_e32 v195, v188
	v_pk_mul_f32 v[178:179], v[178:179], v[182:183]
	v_pk_fma_f32 v[180:181], v[180:181], v[194:195], v[188:189]
	v_pk_mul_f32 v[178:179], v[178:179], v[184:185]
	s_waitcnt lgkmcnt(0)
	v_mov_b32_e32 v187, v190
	v_mov_b32_e32 v179, v181
	v_pk_mul_f32 v[180:181], v[178:179], v[186:187]
	v_pk_fma_f32 v[178:179], v[178:179], v[186:187], v[190:191]
	v_pk_mul_f32 v[180:181], v[180:181], v[188:189]
	v_mov_b32_e32 v182, v190
	v_mov_b32_e32 v178, v180
	v_mov_b32_e32 v183, v192
	v_pk_mul_f32 v[180:181], v[180:181], v[190:191]
	v_pk_fma_f32 v[178:179], v[178:179], v[182:183], v[192:193]
	v_pk_mul_f32 v[180:181], v[180:181], v[192:193]
	v_add_u32_e32 v178, 32, v92
	v_mov_b32_e32 v181, v179
	v_ashrrev_i32_e32 v179, 31, v178
	v_lshl_add_u64 v[178:179], v[178:179], 3, s[24:25]
	global_store_dwordx2 v[178:179], v[180:181], off
.LBB0_346:
	s_or_b64 exec, exec, s[8:9]
	s_waitcnt vmcnt(16)
	ds_read_b32 v251, v167 offset:256
	v_mul_f32_e32 v151, 0xbfb8aa3b, v173
	v_mul_f32_e32 v93, 0xbfb8aa3b, v174
	s_nop 0
	v_fmamk_f32 v18, v18, 0xbfb8aa3b, v151
	v_fmamk_f32 v19, v19, 0xbfb8aa3b, v151
	v_fmamk_f32 v16, v16, 0xbfb8aa3b, v151
	v_fmamk_f32 v32, v32, 0xbfb8aa3b, v93
	v_fmamk_f32 v17, v17, 0xbfb8aa3b, v151
	v_exp_f32_e32 v18, v18
	v_fmamk_f32 v33, v33, 0xbfb8aa3b, v93
	v_exp_f32_e32 v161, v19
	v_exp_f32_e32 v91, v16
	v_exp_f32_e32 v32, v32
	v_exp_f32_e32 v152, v17
	v_exp_f32_e32 v33, v33
	v_add_f32_e32 v162, 1.0, v18
	v_add_f32_e32 v32, 1.0, v32
	v_add_f32_e32 v91, 1.0, v91
	v_add_f32_e32 v33, 1.0, v33
	v_rcp_f32_e32 v164, v32
	v_rcp_f32_e32 v163, v91
	v_rcp_f32_e32 v166, v33
	v_add_f32_e32 v152, 1.0, v152
	v_rcp_f32_e32 v165, v152
	v_fmamk_f32 v34, v34, 0xbfb8aa3b, v93
	v_exp_f32_e32 v34, v34
	v_fmamk_f32 v36, v36, 0xbfb8aa3b, v93
	v_add_f32_e32 v34, 1.0, v34
	v_exp_f32_e32 v36, v36
	s_nop 1
	s_nop 1
	s_waitcnt lgkmcnt(0)
	v_mul_f32_e32 v33, 0x3fb8aa3b, v251
	v_mul_f32_e32 v16, v163, v33
	v_exp_f32_e32 v32, v16
	v_rcp_f32_e32 v16, v162
	v_mul_f32_e32 v17, v165, v33
	v_fma_f32 v18, -v32, v32, 1.0
	v_sqrt_f32_e32 v18, v18
	v_mul_f32_e32 v16, v16, v33
	v_exp_f32_e32 v91, v17
	v_mul_f32_e32 v18, v164, v18
	v_mul_f32_e32 v18, v0, v18
	v_exp_f32_e32 v0, v16
	v_add_f32_e32 v16, 1.0, v161
	v_rcp_f32_e32 v16, v16
	v_fma_f32 v19, -v91, v91, 1.0
	v_sqrt_f32_e32 v19, v19
	v_rcp_f32_e32 v17, v34
	v_mul_f32_e32 v16, v16, v33
	v_exp_f32_e32 v152, v16
	v_fmamk_f32 v16, v20, 0xbfb8aa3b, v151
	v_mul_f32_e32 v34, v166, v19
	v_fmamk_f32 v19, v35, 0xbfb8aa3b, v93
	v_exp_f32_e32 v16, v16
	v_exp_f32_e32 v19, v19
	v_fma_f32 v20, -v152, v152, 1.0
	v_add_f32_e32 v16, 1.0, v16
	v_rcp_f32_e32 v16, v16
	v_add_f32_e32 v19, 1.0, v19
	v_rcp_f32_e32 v19, v19
	v_sqrt_f32_e32 v20, v20
	v_mul_f32_e32 v16, v16, v33
	v_fma_f32 v35, -v0, v0, 1.0
	v_mul_f32_e32 v153, v19, v20
	v_exp_f32_e32 v20, v16
	v_fmamk_f32 v16, v21, 0xbfb8aa3b, v151
	v_exp_f32_e32 v16, v16
	v_sqrt_f32_e32 v35, v35
	v_fma_f32 v19, -v20, v20, 1.0
	v_fmamk_f32 v21, v37, 0xbfb8aa3b, v93
	v_add_f32_e32 v16, 1.0, v16
	v_rcp_f32_e32 v16, v16
	v_mul_f32_e32 v35, v17, v35
	v_add_f32_e32 v17, 1.0, v36
	v_rcp_f32_e32 v17, v17
	v_mul_f32_e32 v16, v16, v33
	v_exp_f32_e32 v36, v16
	v_fmamk_f32 v16, v22, 0xbfb8aa3b, v151
	v_exp_f32_e32 v16, v16
	v_sqrt_f32_e32 v19, v19
	v_exp_f32_e32 v21, v21
	v_add_f32_e32 v16, 1.0, v16
	v_rcp_f32_e32 v16, v16
	v_mul_f32_e32 v17, v17, v19
	v_mul_f32_e32 v19, v4, v17
	v_add_f32_e32 v4, 1.0, v21
	v_fmamk_f32 v21, v38, 0xbfb8aa3b, v93
	v_mul_f32_e32 v16, v16, v33
	v_fma_f32 v17, -v36, v36, 1.0
	v_exp_f32_e32 v21, v21
	v_rcp_f32_e32 v4, v4
	v_sqrt_f32_e32 v17, v17
	v_exp_f32_e32 v37, v16
	v_add_f32_e32 v16, 1.0, v21
	v_fmamk_f32 v21, v23, 0xbfb8aa3b, v151
	v_mul_f32_e32 v4, v4, v17
	v_fma_f32 v17, -v37, v37, 1.0
	v_rcp_f32_e32 v16, v16
	v_sqrt_f32_e32 v17, v17
	v_exp_f32_e32 v21, v21
	v_fmamk_f32 v22, v39, 0xbfb8aa3b, v93
	v_mul_f32_e32 v23, v16, v17
	v_add_f32_e32 v16, 1.0, v21
	v_rcp_f32_e32 v16, v16
	v_fmamk_f32 v21, v24, 0xbfb8aa3b, v151
	v_exp_f32_e32 v21, v21
	v_mul_f32_e32 v16, v16, v33
	v_exp_f32_e32 v24, v16
	v_add_f32_e32 v16, 1.0, v21
	v_rcp_f32_e32 v16, v16
	v_exp_f32_e32 v22, v22
	v_fmamk_f32 v21, v40, 0xbfb8aa3b, v93
	v_mul_f32_e32 v16, v16, v33
	v_add_f32_e32 v17, 1.0, v22
	v_fma_f32 v22, -v24, v24, 1.0
	v_sqrt_f32_e32 v38, v22
	v_exp_f32_e32 v22, v16
	v_fmamk_f32 v16, v25, 0xbfb8aa3b, v151
	v_exp_f32_e32 v16, v16
	v_exp_f32_e32 v21, v21
	v_fmamk_f32 v39, v41, 0xbfb8aa3b, v93
	v_fma_f32 v25, -v22, v22, 1.0
	v_add_f32_e32 v16, 1.0, v16
	v_rcp_f32_e32 v16, v16
	v_add_f32_e32 v21, 1.0, v21
	v_rcp_f32_e32 v17, v17
	v_rcp_f32_e32 v21, v21
	v_sqrt_f32_e32 v25, v25
	v_exp_f32_e32 v39, v39
	v_mul_f32_e32 v16, v16, v33
	v_mul_f32_e32 v38, v17, v38
	v_mul_f32_e32 v17, v21, v25
	v_add_f32_e32 v21, 1.0, v39
	v_exp_f32_e32 v39, v16
	v_fmamk_f32 v16, v26, 0xbfb8aa3b, v151
	v_exp_f32_e32 v16, v16
	v_rcp_f32_e32 v25, v21
	v_fma_f32 v21, -v39, v39, 1.0
	v_sqrt_f32_e32 v26, v21
	v_add_f32_e32 v16, 1.0, v16
	v_fmamk_f32 v21, v42, 0xbfb8aa3b, v93
	v_rcp_f32_e32 v16, v16
	v_exp_f32_e32 v40, v21
	v_mul_f32_e32 v21, v8, v17
	v_mul_f32_e32 v16, v16, v33
	v_add_f32_e32 v17, 1.0, v40
	v_exp_f32_e32 v40, v16
	v_fmamk_f32 v16, v27, 0xbfb8aa3b, v151
	v_exp_f32_e32 v16, v16
	v_mul_f32_e32 v8, v25, v26
	v_fma_f32 v25, -v40, v40, 1.0
	v_fmamk_f32 v26, v43, 0xbfb8aa3b, v93
	v_add_f32_e32 v16, 1.0, v16
	v_rcp_f32_e32 v16, v16
	v_rcp_f32_e32 v17, v17
	v_sqrt_f32_e32 v25, v25
	v_mul_f32_e32 v16, v16, v33
	v_exp_f32_e32 v26, v26
	v_exp_f32_e32 v41, v16
	v_mul_f32_e32 v154, v17, v25
	v_fmamk_f32 v25, v28, 0xbfb8aa3b, v151
	v_add_f32_e32 v16, 1.0, v26
	v_fmamk_f32 v26, v44, 0xbfb8aa3b, v93
	v_fma_f32 v17, -v41, v41, 1.0
	v_exp_f32_e32 v25, v25
	v_rcp_f32_e32 v16, v16
	v_sqrt_f32_e32 v17, v17
	v_exp_f32_e32 v26, v26
	v_add_f32_e32 v25, 1.0, v25
	v_rcp_f32_e32 v25, v25
	v_mul_f32_e32 v155, v16, v17
	v_add_f32_e32 v16, 1.0, v26
	v_fmamk_f32 v26, v45, 0xbfb8aa3b, v93
	v_exp_f32_e32 v26, v26
	v_rcp_f32_e32 v17, v16
	v_mul_f32_e32 v16, v25, v33
	v_fmamk_f32 v25, v29, 0xbfb8aa3b, v151
	v_exp_f32_e32 v25, v25
	v_add_f32_e32 v26, 1.0, v26
	v_rcp_f32_e32 v42, v26
	v_fmamk_f32 v26, v30, 0xbfb8aa3b, v151
	v_exp_f32_e32 v26, v26
	v_add_f32_e32 v25, 1.0, v25
	v_rcp_f32_e32 v25, v25
	v_fmamk_f32 v27, v46, 0xbfb8aa3b, v93
	v_exp_f32_e32 v27, v27
	v_add_f32_e32 v26, 1.0, v26
	v_rcp_f32_e32 v26, v26
	v_mul_f32_e32 v25, v25, v33
	v_exp_f32_e32 v43, v25
	v_add_f32_e32 v25, 1.0, v27
	v_rcp_f32_e32 v44, v25
	v_mul_f32_e32 v25, v26, v33
	v_fmamk_f32 v26, v31, 0xbfb8aa3b, v151
	v_exp_f32_e32 v26, v26
	v_fmamk_f32 v27, v47, 0xbfb8aa3b, v93
	v_exp_f32_e32 v27, v27
	v_add_f32_e32 v26, 1.0, v26
	v_rcp_f32_e32 v26, v26
	v_exp_f32_e32 v16, v16
	v_fmac_f32_e32 v18, 0, v32
	v_exp_f32_e32 v45, v25
	v_add_f32_e32 v25, 1.0, v27
	v_mul_f32_e32 v31, v91, v18
	v_rcp_f32_e32 v46, v25
	v_mul_f32_e32 v25, v26, v33
	v_fmac_f32_e32 v31, v1, v34
	v_mul_f32_e32 v33, v32, v91
	v_fmac_f32_e32 v19, 0, v20
	v_mul_f32_e32 v30, v0, v31
	v_mul_f32_e32 v34, v0, v33
	v_mul_f32_e32 v28, v36, v19
	v_fma_f32 v0, -v16, v16, 1.0
	v_fmac_f32_e32 v28, v5, v4
	v_sqrt_f32_e32 v1, v0
	v_mul_f32_e32 v27, v37, v28
	v_fmac_f32_e32 v30, v2, v35
	v_fmac_f32_e32 v27, v6, v23
	v_fma_f32 v2, -v43, v43, 1.0
	v_mul_f32_e32 v26, v24, v27
	v_mov_b32_e32 v0, v89
	v_sqrt_f32_e32 v2, v2
	v_fmac_f32_e32 v26, v7, v38
	v_pk_mul_f32 v[6:7], v[16:17], v[0:1]
	v_mul_f32_e32 v29, v152, v30
	v_fmac_f32_e32 v6, v12, v7
	v_fmac_f32_e32 v29, v3, v153
	v_mov_b32_e32 v3, v6
	v_pk_mul_f32 v[4:5], v[42:43], v[2:3]
	v_fma_f32 v0, -v45, v45, 1.0
	v_exp_f32_e32 v47, v25
	v_fmac_f32_e32 v5, v13, v4
	v_sqrt_f32_e32 v4, v0
	v_fmac_f32_e32 v21, 0, v22
	v_mul_f32_e32 v25, v39, v21
	v_mul_f32_e32 v36, v20, v36
	v_fmac_f32_e32 v25, v9, v8
	v_pk_mul_f32 v[8:9], v[44:45], v[4:5]
	v_fma_f32 v0, -v47, v47, 1.0
	v_mul_f32_e32 v37, v37, v36
	v_fmac_f32_e32 v9, v14, v8
	v_sqrt_f32_e32 v8, v0
	ds_bpermute_b32 v0, v140, v29
	v_mul_f32_e32 v38, v24, v37
	v_mul_f32_e32 v24, v40, v25
	v_mul_f32_e32 v35, v152, v34
	v_fmac_f32_e32 v24, v10, v154
	v_mul_f32_e32 v23, v41, v24
	ds_bpermute_b32 v13, v140, v35
	v_fmac_f32_e32 v23, v11, v155
	v_pk_mul_f32 v[10:11], v[46:47], v[8:9]
	s_waitcnt lgkmcnt(1)
	v_cndmask_b32_e64 v14, v29, v0, s[0:1]
	v_fmac_f32_e32 v11, v15, v10
	v_cndmask_b32_e64 v10, v0, v29, s[0:1]
	ds_bpermute_b32 v0, v140, v38
	ds_bpermute_b32 v3, v140, v26
	v_mul_f32_e32 v39, v22, v39
	v_mul_f32_e32 v40, v40, v39
	s_waitcnt lgkmcnt(2)
	v_cndmask_b32_e64 v1, v13, v35, s[0:1]
	v_mul_f32_e32 v12, v41, v40
	v_mul_f32_e32 v7, v16, v43
	v_cndmask_b32_e64 v2, v35, v13, s[0:1]
	v_fmac_f32_e32 v10, 0, v1
	v_mul_f32_e32 v4, v45, v7
	v_mul_f32_e32 v15, v35, v13
	v_fmac_f32_e32 v14, v2, v10
	s_waitcnt lgkmcnt(1)
	v_cndmask_b32_e64 v1, v0, v38, s[0:1]
	s_waitcnt lgkmcnt(0)
	v_cndmask_b32_e64 v17, v3, v26, s[0:1]
	v_cndmask_b32_e64 v41, v26, v3, s[0:1]
	ds_bpermute_b32 v2, v140, v12
	ds_bpermute_b32 v3, v140, v23
	v_mul_f32_e32 v8, v47, v4
	v_cndmask_b32_e64 v0, v38, v0, s[0:1]
	v_mul_f32_e32 v42, v15, v1
	v_fmac_f32_e32 v17, v1, v14
	v_mul_f32_e32 v43, v0, v42
	v_fmac_f32_e32 v41, v0, v17
	ds_bpermute_b32 v1, v140, v8
	ds_bpermute_b32 v0, v140, v11
	s_waitcnt lgkmcnt(3)
	v_cndmask_b32_e64 v47, v2, v12, s[0:1]
	s_waitcnt lgkmcnt(2)
	v_cndmask_b32_e64 v44, v3, v23, s[0:1]
	v_cndmask_b32_e64 v2, v12, v2, s[0:1]
	v_cndmask_b32_e64 v45, v23, v3, s[0:1]
	v_mul_f32_e32 v46, v47, v43
	v_fmac_f32_e32 v44, v47, v41
	v_mul_f32_e32 v47, v2, v46
	v_fmac_f32_e32 v45, v2, v44
	s_waitcnt lgkmcnt(1)
	v_cndmask_b32_e64 v2, v1, v8, s[0:1]
	s_waitcnt lgkmcnt(0)
	v_cndmask_b32_e64 v91, v0, v11, s[0:1]
	v_mul_f32_e32 v93, v2, v47
	v_fmac_f32_e32 v91, v2, v45
	s_and_saveexec_b64 s[8:9], s[0:1]
	v_mul_f32_e32 v3, v91, v1
	v_mul_f32_e32 v2, v93, v1
	v_add_f32_e32 v3, v3, v0
	ds_write_b64 v139, v[2:3] offset:4096
	s_or_b64 exec, exec, s[8:9]
	s_and_b64 vcc, exec, s[6:7]
	s_waitcnt lgkmcnt(0)
	s_barrier
	s_cbranch_vccnz .LBB0_353
	s_cmp_lt_u32 s62, 8
	s_cbranch_scc1 .LBB0_354
	s_add_i32 s9, 16, 0x1000
	s_and_b32 s8, s62, 0x7ffffff8
	v_add3_u32 v151, v141, v138, s9
	v_mov_b32_e32 v0, 1.0
	v_mov_b32_e32 v3, 0
	s_mov_b32 s9, 0

.LBB0_357:
	v_mov_b32_e32 v178, v0
	v_mov_b32_e32 v181, v3
	v_mov_b64_e32 v[182:183], v[4:5]
	v_mov_b64_e32 v[184:185], v[6:7]
	v_mov_b64_e32 v[186:187], v[8:9]
	v_mov_b64_e32 v[188:189], v[10:11]
	v_mov_b64_e32 v[190:191], v[12:13]
	v_mov_b64_e32 v[192:193], v[14:15]
	v_mov_b64_e32 v[194:195], v[16:17]
	v_mov_b64_e32 v[196:197], v[18:19]
	v_mov_b64_e32 v[198:199], v[20:21]
	v_mov_b64_e32 v[200:201], v[22:23]
	v_mov_b64_e32 v[202:203], v[24:25]
	v_mov_b64_e32 v[204:205], v[26:27]
	v_mov_b64_e32 v[206:207], v[28:29]
	v_mov_b64_e32 v[208:209], v[30:31]
	v_mov_b64_e32 v[210:211], v[32:33]
	v_mov_b64_e32 v[212:213], v[34:35]
	v_mov_b64_e32 v[214:215], v[36:37]
	v_mov_b64_e32 v[216:217], v[38:39]
	v_mov_b64_e32 v[218:219], v[40:41]
	v_mov_b64_e32 v[220:221], v[42:43]
	v_mov_b64_e32 v[222:223], v[44:45]
	v_mov_b64_e32 v[238:239], v[46:47]
	s_setprio 1
	ds_read_b128 v[0:3], v148 offset:40960
	ds_read_b128 v[4:7], v150 offset:40960
	v_add_u32_e32 v8, 0xa000, v150
	s_waitcnt lgkmcnt(1)
	v_mfma_f32_32x32x16_bf16 v[16:31], v[48:51], v[0:3], 0
	v_cndmask_b32_e64 v179, v191, 1.0, s[0:1]
	v_cndmask_b32_e64 v180, v188, 0, s[0:1]
	v_cndmask_b32_e64 v188, v220, v193, s[0:1]
	v_cndmask_b32_e64 v191, v195, v192, s[0:1]
	v_cndmask_b32_e64 v192, v238, v221, s[0:1]
	v_cndmask_b32_e64 v193, v222, v219, s[0:1]
	v_cndmask_b32_e64 v195, v93, v239, s[0:1]
	v_add_u32_e32 v0, 0xa000, v148
	ds_read_b128 v[0:3], v0 offset:32768
	ds_read_b128 v[8:11], v8 offset:32768
	s_waitcnt lgkmcnt(1)
	v_mfma_f32_32x32x16_bf16 v[32:47], v[48:51], v[0:3], 0
	v_cndmask_b32_e64 v219, v91, v223, s[0:1]
	v_fmac_f32_e32 v196, v210, v180
	v_mul_f32_e32 v210, v179, v210
	v_fmac_f32_e32 v209, v211, v180
	v_mul_f32_e32 v211, v179, v211
	v_fmac_f32_e32 v208, v212, v180
	v_mul_f32_e32 v212, v179, v212
	v_mfma_f32_32x32x16_bf16 v[16:31], v[52:55], v[4:7], v[16:31]
	v_fmac_f32_e32 v207, v213, v180
	v_mul_f32_e32 v179, v179, v213
	v_fmac_f32_e32 v205, v215, v191
	v_mul_f32_e32 v213, v215, v188
	v_fmac_f32_e32 v202, v218, v193
	v_mul_f32_e32 v215, v218, v192
	v_fmac_f32_e32 v187, v182, v219
	ds_read_b128 v[0:3], v145 offset:40960
	ds_read_b128 v[4:7], v149 offset:40960
	s_waitcnt lgkmcnt(2)
	v_mfma_f32_32x32x16_bf16 v[32:47], v[52:55], v[8:11], v[32:47]
	v_mul_f32_e32 v218, v182, v195
	v_mul_f32_e32 v182, v210, v178
	v_fmac_f32_e32 v196, v210, v181
	v_cvt_pk_bf16_f32 v182, v196, v182
	v_fmac_f32_e32 v197, v198, v191
	v_mul_f32_e32 v180, v198, v188
	v_fmac_f32_e32 v206, v214, v191
	v_add_u32_e32 v8, 0xa000, v149
	ds_read_b128 v[8:11], v8 offset:32768
	s_waitcnt lgkmcnt(2)
	v_mfma_f32_32x32x16_bf16 v[16:31], v[56:59], v[0:3], v[16:31]
	v_mul_f32_e32 v198, v214, v188
	v_fmac_f32_e32 v204, v216, v191
	v_mul_f32_e32 v188, v216, v188
	v_fmac_f32_e32 v201, v190, v193
	v_mul_f32_e32 v216, v190, v192
	v_lshl_add_u64 v[190:191], v[94:95], 0, s[48:49]
	global_load_dword v172, v[130:131], off offset:384
	v_add_u32_e32 v0, 0xa000, v145
	ds_read_b128 v[0:3], v0 offset:32768
	s_waitcnt lgkmcnt(0)
	v_mfma_f32_32x32x16_bf16 v[32:47], v[56:59], v[0:3], v[32:47]
	global_load_dword v173, v[126:127], off offset:384
	global_load_dword v174, v[128:129], off offset:384
	global_store_dword v[96:97], v182, off offset:256 nt
	v_mul_f32_e32 v182, v211, v178
	v_fmac_f32_e32 v199, v200, v193
	v_mul_f32_e32 v200, v200, v192
	v_fmac_f32_e32 v203, v217, v193
	v_mfma_f32_32x32x16_bf16 v[16:31], v[60:63], v[4:7], v[16:31]
	v_mul_f32_e32 v214, v217, v192
	v_fmac_f32_e32 v209, v211, v181
	v_cvt_pk_bf16_f32 v182, v209, v182
	v_lshl_add_u64 v[192:193], v[190:191], 0, v[88:89]
	global_store_dword v[192:193], v182, off nt
	v_mul_f32_e32 v182, v212, v178
	v_lshl_add_u64 v[192:193], v[190:191], 0, v[98:99]
	ds_read_b128 v[0:3], v144 offset:40960
	ds_read_b128 v[4:7], v147 offset:40960
	v_mfma_f32_32x32x16_bf16 v[32:47], v[60:63], v[8:11], v[32:47]
	v_fmac_f32_e32 v207, v179, v181
	v_mul_f32_e32 v179, v179, v178
	v_fmac_f32_e32 v208, v212, v181
	v_cvt_pk_bf16_f32 v182, v208, v182
	global_store_dword v[192:193], v182, off nt
	v_cvt_pk_bf16_f32 v179, v207, v179
	v_lshl_add_u64 v[192:193], v[190:191], 0, v[100:101]
	v_add_u32_e32 v8, 0xa000, v147
	ds_read_b128 v[8:11], v8 offset:32768
	s_waitcnt lgkmcnt(2)
	v_mfma_f32_32x32x16_bf16 v[16:31], v[64:67], v[0:3], v[16:31]
	global_store_dword v[192:193], v179, off nt
	v_mul_f32_e32 v179, v180, v178
	v_fmac_f32_e32 v197, v180, v181
	v_cvt_pk_bf16_f32 v179, v197, v179
	v_lshl_add_u64 v[192:193], v[190:191], 0, v[102:103]
	global_store_dword v[192:193], v179, off nt
	v_mul_f32_e32 v179, v198, v178
	v_add_u32_e32 v0, 0xa000, v144
	ds_read_b128 v[0:3], v0 offset:32768
	s_waitcnt lgkmcnt(0)
	v_mfma_f32_32x32x16_bf16 v[32:47], v[64:67], v[0:3], v[32:47]
	v_fmac_f32_e32 v206, v198, v181
	v_cvt_pk_bf16_f32 v179, v206, v179
	v_lshl_add_u64 v[192:193], v[190:191], 0, v[104:105]
	global_store_dword v[192:193], v179, off nt
	v_mul_f32_e32 v179, v213, v178
	v_fmac_f32_e32 v205, v213, v181
	v_cvt_pk_bf16_f32 v179, v205, v179
	v_mfma_f32_32x32x16_bf16 v[16:31], v[68:71], v[4:7], v[16:31]
	v_lshl_add_u64 v[192:193], v[190:191], 0, v[106:107]
	global_store_dword v[192:193], v179, off nt
	v_mul_f32_e32 v179, v188, v178
	v_fmac_f32_e32 v204, v188, v181
	v_cvt_pk_bf16_f32 v179, v204, v179
	v_lshl_add_u64 v[192:193], v[190:191], 0, v[108:109]
	global_store_dword v[192:193], v179, off nt
	ds_read_b128 v[0:3], v143 offset:40960
	ds_read_b128 v[4:7], v146 offset:40960
	v_mfma_f32_32x32x16_bf16 v[32:47], v[68:71], v[8:11], v[32:47]
	v_mul_f32_e32 v179, v200, v178
	v_fmac_f32_e32 v199, v200, v181
	v_cvt_pk_bf16_f32 v179, v199, v179
	v_lshl_add_u64 v[192:193], v[190:191], 0, v[110:111]
	global_store_dword v[192:193], v179, off nt
	v_mul_f32_e32 v179, v214, v178
	v_fmac_f32_e32 v203, v214, v181
	v_add_u32_e32 v8, 0xa000, v146
	ds_read_b128 v[8:11], v8 offset:32768
	s_waitcnt lgkmcnt(2)
	v_mfma_f32_32x32x16_bf16 v[16:31], v[72:75], v[0:3], v[16:31]
	v_cvt_pk_bf16_f32 v179, v203, v179
	v_lshl_add_u64 v[192:193], v[190:191], 0, v[112:113]
	global_store_dword v[192:193], v179, off nt
	v_mul_f32_e32 v179, v215, v178
	v_fmac_f32_e32 v202, v215, v181
	v_cvt_pk_bf16_f32 v179, v202, v179
	v_lshl_add_u64 v[192:193], v[190:191], 0, v[114:115]
	v_add_u32_e32 v0, 0xa000, v143
	ds_read_b128 v[0:3], v0 offset:32768
	s_waitcnt lgkmcnt(0)
	v_mfma_f32_32x32x16_bf16 v[32:47], v[72:75], v[0:3], v[32:47]
	global_store_dword v[192:193], v179, off nt
	v_mul_f32_e32 v179, v216, v178
	v_fmac_f32_e32 v184, v194, v219
	v_mul_f32_e32 v194, v194, v195
	v_fmac_f32_e32 v201, v216, v181
	v_cvt_pk_bf16_f32 v179, v201, v179
	v_lshl_add_u64 v[192:193], v[190:191], 0, v[116:117]
	v_mfma_f32_32x32x16_bf16 v[16:31], v[76:79], v[4:7], v[16:31]
	global_store_dword v[192:193], v179, off nt
	v_fmac_f32_e32 v184, v194, v181
	v_mul_f32_e32 v179, v194, v178
	v_fmac_f32_e32 v183, v185, v219
	v_mul_f32_e32 v217, v185, v195
	v_cvt_pk_bf16_f32 v179, v184, v179
	v_lshl_add_u64 v[184:185], v[190:191], 0, v[118:119]
	v_mfma_f32_32x32x16_bf16 v[32:47], v[76:79], v[8:11], v[32:47]
	global_store_dword v[184:185], v179, off nt
	v_fmac_f32_e32 v183, v217, v181
	v_mul_f32_e32 v179, v217, v178
	v_cvt_pk_bf16_f32 v179, v183, v179
	v_lshl_add_u64 v[182:183], v[190:191], 0, v[120:121]
	v_fmac_f32_e32 v189, v186, v219
	v_mul_f32_e32 v186, v186, v195
	v_mfma_f32_32x32x16_bf16 v[0:15], v[72:75], v[80:83], 0
	global_store_dword v[182:183], v179, off nt
	v_mul_f32_e32 v179, v218, v178
	v_fmac_f32_e32 v187, v218, v181
	v_cvt_pk_bf16_f32 v179, v187, v179
	v_lshl_add_u64 v[182:183], v[190:191], 0, v[122:123]
	v_mul_f32_e32 v178, v186, v178
	global_store_dword v[182:183], v179, off nt
	v_mfma_f32_32x32x16_bf16 v[0:15], v[76:79], v[84:87], v[0:15]
	v_fmac_f32_e32 v189, v186, v181
	v_cvt_pk_bf16_f32 v180, v189, v178
	v_lshl_add_u64 v[178:179], v[190:191], 0, v[124:125]
	global_store_dword v[178:179], v180, off nt
	s_setprio 0
	s_and_saveexec_b64 s[8:9], s[4:5]
	s_cbranch_execz .LBB0_359
	v_add_u32_e32 v190, 0x1000, v142
	ds_read2_b64 v[178:181], v190 offset1:32
	ds_read2_b64 v[182:185], v190 offset0:64 offset1:96
	ds_read2_b64 v[186:189], v190 offset0:128 offset1:160
	ds_read2_b64 v[190:193], v190 offset0:192 offset1:224
	s_waitcnt lgkmcnt(3)
	v_fma_f32 v194, 0, v178, v179
	v_pk_mul_f32 v[178:179], v[178:179], v[180:181]
	v_fma_f32 v180, v180, v194, v181
	s_waitcnt lgkmcnt(2)
	v_fma_f32 v180, v182, v180, v183
	v_fma_f32 v180, v184, v180, v185
	s_waitcnt lgkmcnt(1)
	v_fma_f32 v181, v186, v180, v187
	v_mov_b32_e32 v180, v178
	v_mov_b32_e32 v194, v182
	v_mov_b32_e32 v195, v188
	v_pk_mul_f32 v[178:179], v[178:179], v[182:183]
	v_pk_fma_f32 v[180:181], v[180:181], v[194:195], v[188:189]
	v_pk_mul_f32 v[178:179], v[178:179], v[184:185]
	s_waitcnt lgkmcnt(0)
	v_mov_b32_e32 v187, v190
	v_mov_b32_e32 v179, v181
	v_pk_mul_f32 v[180:181], v[178:179], v[186:187]
	v_pk_fma_f32 v[178:179], v[178:179], v[186:187], v[190:191]
	v_pk_mul_f32 v[180:181], v[180:181], v[188:189]
	v_mov_b32_e32 v182, v190
	v_mov_b32_e32 v178, v180
	v_mov_b32_e32 v183, v192
	v_pk_mul_f32 v[180:181], v[180:181], v[190:191]
	v_pk_fma_f32 v[178:179], v[178:179], v[182:183], v[192:193]
	v_pk_mul_f32 v[180:181], v[180:181], v[192:193]
	v_add_u32_e32 v178, 64, v92
	v_mov_b32_e32 v181, v179
	v_ashrrev_i32_e32 v179, 31, v178
	v_lshl_add_u64 v[178:179], v[178:179], 3, s[24:25]
	global_store_dwordx2 v[178:179], v[180:181], off
.LBB0_359:
	s_or_b64 exec, exec, s[8:9]
	s_waitcnt vmcnt(16)
	ds_read_b32 v251, v167 offset:384
	v_mul_f32_e32 v49, 0xbfb8aa3b, v173
	v_mul_f32_e32 v48, 0xbfb8aa3b, v174
	s_nop 0
	v_fmamk_f32 v18, v18, 0xbfb8aa3b, v49
	v_fmamk_f32 v19, v19, 0xbfb8aa3b, v49
	v_fmamk_f32 v16, v16, 0xbfb8aa3b, v49
	v_fmamk_f32 v32, v32, 0xbfb8aa3b, v48
	v_fmamk_f32 v17, v17, 0xbfb8aa3b, v49
	v_exp_f32_e32 v18, v18
	v_fmamk_f32 v33, v33, 0xbfb8aa3b, v48
	v_exp_f32_e32 v59, v19
	v_exp_f32_e32 v50, v16
	v_exp_f32_e32 v32, v32
	v_exp_f32_e32 v51, v17
	v_exp_f32_e32 v33, v33
	v_add_f32_e32 v60, 1.0, v18
	v_add_f32_e32 v32, 1.0, v32
	v_add_f32_e32 v50, 1.0, v50
	v_add_f32_e32 v33, 1.0, v33
	v_rcp_f32_e32 v62, v32
	v_rcp_f32_e32 v61, v50
	v_rcp_f32_e32 v64, v33
	v_add_f32_e32 v51, 1.0, v51
	v_rcp_f32_e32 v63, v51
	v_fmamk_f32 v34, v34, 0xbfb8aa3b, v48
	v_exp_f32_e32 v34, v34
	v_fmamk_f32 v36, v36, 0xbfb8aa3b, v48
	v_add_f32_e32 v34, 1.0, v34
	v_exp_f32_e32 v36, v36
	s_nop 1
	s_nop 1
	s_waitcnt lgkmcnt(0)
	v_mul_f32_e32 v33, 0x3fb8aa3b, v251
	v_mul_f32_e32 v16, v61, v33
	v_exp_f32_e32 v32, v16
	v_rcp_f32_e32 v16, v60
	v_mul_f32_e32 v17, v63, v33
	v_fma_f32 v18, -v32, v32, 1.0
	v_sqrt_f32_e32 v18, v18
	v_mul_f32_e32 v16, v16, v33
	v_exp_f32_e32 v50, v17
	v_mul_f32_e32 v18, v62, v18
	v_mul_f32_e32 v18, v0, v18
	v_exp_f32_e32 v0, v16
	v_add_f32_e32 v16, 1.0, v59
	v_rcp_f32_e32 v16, v16
	v_fma_f32 v19, -v50, v50, 1.0
	v_sqrt_f32_e32 v19, v19
	v_rcp_f32_e32 v17, v34
	v_mul_f32_e32 v16, v16, v33
	v_exp_f32_e32 v51, v16
	v_fmamk_f32 v16, v20, 0xbfb8aa3b, v49
	v_mul_f32_e32 v34, v64, v19
	v_fmamk_f32 v19, v35, 0xbfb8aa3b, v48
	v_exp_f32_e32 v16, v16
	v_exp_f32_e32 v19, v19
	v_fma_f32 v20, -v51, v51, 1.0
	v_add_f32_e32 v16, 1.0, v16
	v_rcp_f32_e32 v16, v16
	v_add_f32_e32 v19, 1.0, v19
	v_rcp_f32_e32 v19, v19
	v_sqrt_f32_e32 v20, v20
	v_mul_f32_e32 v16, v16, v33
	v_fma_f32 v35, -v0, v0, 1.0
	v_mul_f32_e32 v52, v19, v20
	v_exp_f32_e32 v20, v16
	v_fmamk_f32 v16, v21, 0xbfb8aa3b, v49
	v_exp_f32_e32 v16, v16
	v_sqrt_f32_e32 v35, v35
	v_fma_f32 v19, -v20, v20, 1.0
	v_fmamk_f32 v21, v37, 0xbfb8aa3b, v48
	v_add_f32_e32 v16, 1.0, v16
	v_rcp_f32_e32 v16, v16
	v_mul_f32_e32 v35, v17, v35
	v_add_f32_e32 v17, 1.0, v36
	v_rcp_f32_e32 v17, v17
	v_mul_f32_e32 v16, v16, v33
	v_exp_f32_e32 v36, v16
	v_fmamk_f32 v16, v22, 0xbfb8aa3b, v49
	v_exp_f32_e32 v16, v16
	v_sqrt_f32_e32 v19, v19
	v_exp_f32_e32 v21, v21
	v_add_f32_e32 v16, 1.0, v16
	v_rcp_f32_e32 v16, v16
	v_mul_f32_e32 v17, v17, v19
	v_mul_f32_e32 v19, v4, v17
	v_add_f32_e32 v4, 1.0, v21
	v_fmamk_f32 v21, v38, 0xbfb8aa3b, v48
	v_mul_f32_e32 v16, v16, v33
	v_fma_f32 v17, -v36, v36, 1.0
	v_exp_f32_e32 v21, v21
	v_rcp_f32_e32 v4, v4
	v_sqrt_f32_e32 v17, v17
	v_exp_f32_e32 v37, v16
	v_add_f32_e32 v16, 1.0, v21
	v_fmamk_f32 v21, v23, 0xbfb8aa3b, v49
	v_mul_f32_e32 v4, v4, v17
	v_fma_f32 v17, -v37, v37, 1.0
	v_rcp_f32_e32 v16, v16
	v_sqrt_f32_e32 v17, v17
	v_exp_f32_e32 v21, v21
	v_fmamk_f32 v22, v39, 0xbfb8aa3b, v48
	v_mul_f32_e32 v23, v16, v17
	v_add_f32_e32 v16, 1.0, v21
	v_rcp_f32_e32 v16, v16
	v_fmamk_f32 v21, v24, 0xbfb8aa3b, v49
	v_exp_f32_e32 v21, v21
	v_mul_f32_e32 v16, v16, v33
	v_exp_f32_e32 v24, v16
	v_add_f32_e32 v16, 1.0, v21
	v_rcp_f32_e32 v16, v16
	v_exp_f32_e32 v22, v22
	v_fmamk_f32 v21, v40, 0xbfb8aa3b, v48
	v_mul_f32_e32 v16, v16, v33
	v_add_f32_e32 v17, 1.0, v22
	v_fma_f32 v22, -v24, v24, 1.0
	v_sqrt_f32_e32 v38, v22
	v_exp_f32_e32 v22, v16
	v_fmamk_f32 v16, v25, 0xbfb8aa3b, v49
	v_exp_f32_e32 v16, v16
	v_exp_f32_e32 v21, v21
	v_fmamk_f32 v39, v41, 0xbfb8aa3b, v48
	v_fma_f32 v25, -v22, v22, 1.0
	v_add_f32_e32 v16, 1.0, v16
	v_rcp_f32_e32 v16, v16
	v_add_f32_e32 v21, 1.0, v21
	v_rcp_f32_e32 v17, v17
	v_rcp_f32_e32 v21, v21
	v_sqrt_f32_e32 v25, v25
	v_exp_f32_e32 v39, v39
	v_mul_f32_e32 v16, v16, v33
	v_mul_f32_e32 v38, v17, v38
	v_mul_f32_e32 v17, v21, v25
	v_add_f32_e32 v21, 1.0, v39
	v_exp_f32_e32 v39, v16
	v_fmamk_f32 v16, v26, 0xbfb8aa3b, v49
	v_exp_f32_e32 v16, v16
	v_rcp_f32_e32 v25, v21
	v_fma_f32 v21, -v39, v39, 1.0
	v_sqrt_f32_e32 v26, v21
	v_add_f32_e32 v16, 1.0, v16
	v_fmamk_f32 v21, v42, 0xbfb8aa3b, v48
	v_rcp_f32_e32 v16, v16
	v_exp_f32_e32 v40, v21
	v_mul_f32_e32 v21, v8, v17
	v_mul_f32_e32 v16, v16, v33
	v_add_f32_e32 v17, 1.0, v40
	v_exp_f32_e32 v40, v16
	v_fmamk_f32 v16, v27, 0xbfb8aa3b, v49
	v_exp_f32_e32 v16, v16
	v_mul_f32_e32 v8, v25, v26
	v_fma_f32 v25, -v40, v40, 1.0
	v_fmamk_f32 v26, v43, 0xbfb8aa3b, v48
	v_add_f32_e32 v16, 1.0, v16
	v_rcp_f32_e32 v16, v16
	v_rcp_f32_e32 v17, v17
	v_sqrt_f32_e32 v25, v25
	v_mul_f32_e32 v16, v16, v33
	v_exp_f32_e32 v26, v26
	v_exp_f32_e32 v41, v16
	v_mul_f32_e32 v53, v17, v25
	v_fmamk_f32 v25, v28, 0xbfb8aa3b, v49
	v_add_f32_e32 v16, 1.0, v26
	v_fmamk_f32 v26, v44, 0xbfb8aa3b, v48
	v_fma_f32 v17, -v41, v41, 1.0
	v_exp_f32_e32 v25, v25
	v_rcp_f32_e32 v16, v16
	v_sqrt_f32_e32 v17, v17
	v_exp_f32_e32 v26, v26
	v_add_f32_e32 v25, 1.0, v25
	v_rcp_f32_e32 v25, v25
	v_mul_f32_e32 v54, v16, v17
	v_add_f32_e32 v16, 1.0, v26
	v_fmamk_f32 v26, v45, 0xbfb8aa3b, v48
	v_exp_f32_e32 v26, v26
	v_rcp_f32_e32 v17, v16
	v_mul_f32_e32 v16, v25, v33
	v_fmamk_f32 v25, v29, 0xbfb8aa3b, v49
	v_exp_f32_e32 v25, v25
	v_add_f32_e32 v26, 1.0, v26
	v_rcp_f32_e32 v42, v26
	v_fmamk_f32 v26, v30, 0xbfb8aa3b, v49
	v_exp_f32_e32 v26, v26
	v_add_f32_e32 v25, 1.0, v25
	v_rcp_f32_e32 v25, v25
	v_fmamk_f32 v27, v46, 0xbfb8aa3b, v48
	v_exp_f32_e32 v27, v27
	v_add_f32_e32 v26, 1.0, v26
	v_rcp_f32_e32 v26, v26
	v_mul_f32_e32 v25, v25, v33
	v_exp_f32_e32 v43, v25
	v_add_f32_e32 v25, 1.0, v27
	v_rcp_f32_e32 v44, v25
	v_mul_f32_e32 v25, v26, v33
	v_fmamk_f32 v26, v31, 0xbfb8aa3b, v49
	v_exp_f32_e32 v26, v26
	v_fmamk_f32 v27, v47, 0xbfb8aa3b, v48
	v_exp_f32_e32 v27, v27
	v_add_f32_e32 v26, 1.0, v26
	v_rcp_f32_e32 v26, v26
	v_exp_f32_e32 v16, v16
	v_fmac_f32_e32 v18, 0, v32
	v_exp_f32_e32 v45, v25
	v_add_f32_e32 v25, 1.0, v27
	v_mul_f32_e32 v31, v50, v18
	v_rcp_f32_e32 v46, v25
	v_mul_f32_e32 v25, v26, v33
	v_fmac_f32_e32 v31, v1, v34
	v_mul_f32_e32 v33, v32, v50
	v_fmac_f32_e32 v19, 0, v20
	v_mul_f32_e32 v30, v0, v31
	v_mul_f32_e32 v34, v0, v33
	v_mul_f32_e32 v28, v36, v19
	v_fma_f32 v0, -v16, v16, 1.0
	v_fmac_f32_e32 v28, v5, v4
	v_sqrt_f32_e32 v1, v0
	v_mul_f32_e32 v27, v37, v28
	v_fmac_f32_e32 v30, v2, v35
	v_fmac_f32_e32 v27, v6, v23
	v_fma_f32 v2, -v43, v43, 1.0
	v_mul_f32_e32 v26, v24, v27
	v_mov_b32_e32 v0, v89
	v_sqrt_f32_e32 v2, v2
	v_fmac_f32_e32 v26, v7, v38
	v_pk_mul_f32 v[6:7], v[16:17], v[0:1]
	v_mul_f32_e32 v29, v51, v30
	v_fmac_f32_e32 v6, v12, v7
	v_fmac_f32_e32 v29, v3, v52
	v_mov_b32_e32 v3, v6
	v_pk_mul_f32 v[4:5], v[42:43], v[2:3]
	v_fma_f32 v0, -v45, v45, 1.0
	v_exp_f32_e32 v47, v25
	v_fmac_f32_e32 v5, v13, v4
	v_sqrt_f32_e32 v4, v0
	v_fmac_f32_e32 v21, 0, v22
	v_mul_f32_e32 v25, v39, v21
	v_mul_f32_e32 v36, v20, v36
	v_fmac_f32_e32 v25, v9, v8
	v_pk_mul_f32 v[8:9], v[44:45], v[4:5]
	v_fma_f32 v0, -v47, v47, 1.0
	v_mul_f32_e32 v37, v37, v36
	v_fmac_f32_e32 v9, v14, v8
	v_sqrt_f32_e32 v8, v0
	ds_bpermute_b32 v0, v140, v29
	v_mul_f32_e32 v38, v24, v37
	v_mul_f32_e32 v24, v40, v25
	v_mul_f32_e32 v35, v51, v34
	v_fmac_f32_e32 v24, v10, v53
	v_mul_f32_e32 v23, v41, v24
	ds_bpermute_b32 v13, v140, v35
	v_fmac_f32_e32 v23, v11, v54
	v_pk_mul_f32 v[10:11], v[46:47], v[8:9]
	s_waitcnt lgkmcnt(1)
	v_cndmask_b32_e64 v14, v29, v0, s[0:1]
	v_fmac_f32_e32 v11, v15, v10
	v_cndmask_b32_e64 v10, v0, v29, s[0:1]
	ds_bpermute_b32 v0, v140, v38
	ds_bpermute_b32 v3, v140, v26
	v_mul_f32_e32 v39, v22, v39
	v_mul_f32_e32 v40, v40, v39
	s_waitcnt lgkmcnt(2)
	v_cndmask_b32_e64 v1, v13, v35, s[0:1]
	v_mul_f32_e32 v12, v41, v40
	v_mul_f32_e32 v7, v16, v43
	v_cndmask_b32_e64 v2, v35, v13, s[0:1]
	v_fmac_f32_e32 v10, 0, v1
	v_mul_f32_e32 v4, v45, v7
	v_mul_f32_e32 v15, v35, v13
	v_fmac_f32_e32 v14, v2, v10
	s_waitcnt lgkmcnt(1)
	v_cndmask_b32_e64 v1, v0, v38, s[0:1]
	s_waitcnt lgkmcnt(0)
	v_cndmask_b32_e64 v17, v3, v26, s[0:1]
	v_cndmask_b32_e64 v41, v26, v3, s[0:1]
	ds_bpermute_b32 v2, v140, v12
	ds_bpermute_b32 v3, v140, v23
	v_mul_f32_e32 v8, v47, v4
	v_cndmask_b32_e64 v0, v38, v0, s[0:1]
	v_mul_f32_e32 v42, v15, v1
	v_fmac_f32_e32 v17, v1, v14
	v_mul_f32_e32 v43, v0, v42
	v_fmac_f32_e32 v41, v0, v17
	ds_bpermute_b32 v1, v140, v8
	ds_bpermute_b32 v0, v140, v11
	s_waitcnt lgkmcnt(3)
	v_cndmask_b32_e64 v47, v2, v12, s[0:1]
	s_waitcnt lgkmcnt(2)
	v_cndmask_b32_e64 v44, v3, v23, s[0:1]
	v_cndmask_b32_e64 v2, v12, v2, s[0:1]
	v_cndmask_b32_e64 v45, v23, v3, s[0:1]
	v_mul_f32_e32 v46, v47, v43
	v_fmac_f32_e32 v44, v47, v41
	v_mul_f32_e32 v47, v2, v46
	v_fmac_f32_e32 v45, v2, v44
	s_waitcnt lgkmcnt(1)
	v_cndmask_b32_e64 v2, v1, v8, s[0:1]
	s_waitcnt lgkmcnt(0)
	v_cndmask_b32_e64 v48, v0, v11, s[0:1]
	v_mul_f32_e32 v49, v2, v47
	v_fmac_f32_e32 v48, v2, v45
	s_and_saveexec_b64 s[8:9], s[0:1]
	v_mul_f32_e32 v3, v48, v1
	v_mul_f32_e32 v2, v49, v1
	v_add_f32_e32 v3, v3, v0
	ds_write_b64 v139, v[2:3] offset:6144
	s_or_b64 exec, exec, s[8:9]
	s_and_b64 vcc, exec, s[6:7]
	s_waitcnt lgkmcnt(0)
	s_barrier
	s_cbranch_vccnz .LBB0_366
	s_cmp_lt_u32 s62, 8
	s_cbranch_scc1 .LBB0_367
	s_and_b32 s6, s62, 0x7ffffff8
	v_add3_u32 v50, v141, v138, s88
	v_mov_b32_e32 v0, 1.0
	v_mov_b32_e32 v3, 0
	s_mov_b32 s7, 0
